# diff mainloop: incremental ring offsets and global row offsets kept in SGPRs, fewer counted LDS waits, lead V fragments pre-read before the barrier
# baseline (speedup 1.0000x reference)
; DI void phase_diff(KP p, int layer, u16* sm) {
;     ...
;     uint4 kra, krb; uint2 vra, vrb;
;     const int key0 = tid >> 3, ch = tid & 7;
;     const u16* kg = prow + (size_t)key0 * NPROJ + 256 + head * 64 + ch * 8;
;     const unsigned char* vg = p.vt8 + ((size_t)bh * 64 + key0) * S + ch * 8;
;     auto gload = [&](int st) __attribute__((always_inline)) {
;       const int t0 = (st & 127) * 2;
;       kra = *(const uint4*)(kg + (size_t)(t0 * 64) * NPROJ); krb = *(const uint4*)(kg + (size_t)(t0 * 64 + 64) * NPROJ);
;       vra = *(const uint2*)(vg + t0 * 64); vrb = *(const uint2*)(vg + t0 * 64 + 64);
;     };
;     auto lstore = [&](int buf) __attribute__((always_inline)) {
;       u16* kd = Ks + buf * (2 * KS_BUF) + key0 * KS_STRIDE + ch * 8;
;       *(uint4*)kd = kra; *(uint4*)(kd + KS_BUF) = krb;
;       unsigned char* vd = Vl + buf * (2 * VL_BUF) + key0 * VL_STRIDE + 4 * ch;
;       *(unsigned*)vd = vra.x; *(unsigned*)(vd + 32) = vra.y;
;       *(unsigned*)(vd + VL_BUF) = vrb.x; *(unsigned*)(vd + VL_BUF + 32) = vrb.y;
;     };
;     gload(0); lstore(0);
;     __syncthreads();
;     if (w >= 4) __builtin_amdgcn_s_setprio(1);
;     auto tile_loop = [&](auto shifted) __attribute__((always_inline)) {
;       constexpr bool SH = decltype(shifted)::value;
;       for (int st = 0; st < 128; ++st) {
;         const int buf = st & 1;
;         gload(st + 1);
; #pragma unroll
;         for (int hf = 0; hf < 2; ++hf) {
;           const u16* Kt = Ks + buf * (2 * KS_BUF) + hf * KS_BUF;
;           const unsigned char* Vt = Vl + buf * (2 * VL_BUF) + hf * VL_BUF;
;           f32x16 Sc[2][2];
; #pragma unroll
;           for (int sub = 0; sub < 2; ++sub)
; #pragma unroll
;             for (int m = 0; m < 2; ++m) {
; #pragma unroll
;               for (int i = 0; i < 16; ++i) Sc[sub][m][i] = cneg[i];
; #pragma unroll
;               for (int s = 0; s < 2; ++s) {
;                 const bf16x8 kf = *(const bf16x8*)(Kt + (sub * 32 + r) * KS_STRIDE + m * 32 + s * 16 + 8 * hh);
;                 Sc[sub][m] = MFMA32(kf, qf[m][s], Sc[sub][m]);
;               }
;             }
;           v8i_t pf[2];
; #pragma unroll
;           for (int sub = 0; sub < 2; ++sub)
; #pragma unroll
;             for (int m = 0; m < 2; ++m)
; #pragma unroll
;               for (int g = 0; g < 4; ++g) {
;                 float pv[4];
; #pragma unroll
.Ldiff_common:
	v_lshlrev_b32_e32 v16, 1, v252
	v_add_u32_e32 v16, v16, v0
	v_add_u32_e32 v17, v253, v230
	global_load_dwordx2 v[222:223], v[218:219], off
	global_load_dwordx2 v[220:221], v[218:219], off offset:64
	s_mov_b32 s18, 0xc0000
	s_mov_b32 s19, s13
	v_lshl_add_u64 v[80:81], v[216:217], 0, s[18:19]
	global_load_dwordx4 v[188:191], v[80:81], off offset:512
	v_add_u32_e32 v82, 0x12000, v251
	v_add_u32_e32 v83, 0x13400, v251
	v_add_u32_e32 v84, 0x4800, v250
	s_waitcnt vmcnt(2)
	ds_write2_b32 v82, v222, v223 offset1:8
	s_waitcnt vmcnt(1)
	ds_write2_b32 v83, v220, v221 offset1:8
	s_waitcnt vmcnt(0)
	ds_write_b128 v84, v[188:191]
	s_mov_b32 s6, 0
	s_mov_b32 s98, 0
	s_movk_i32 s100, 0x4800
	s_mov_b32 s99, 0x9000
	s_mov_b32 s101, 0x14800
	s_movk_i32 s16, 0x80
	s_movk_i32 s17, 0x100
	v_mov_b32_e32 v18, v16
	v_add_u32_e32 v20, 0x12000, v17
	s_waitcnt lgkmcnt(0)
	s_barrier
	s_and_b64 vcc, exec, s[28:29]
	s_cbranch_vccnz .Ldiff_lag_entry
	v_mov_b32_e32 v144, 0
	v_mov_b32_e32 v145, 0
	v_mov_b32_e32 v146, 0
	v_mov_b32_e32 v147, 0
	v_mov_b32_e32 v148, 0
	v_mov_b32_e32 v149, 0
	v_mov_b32_e32 v150, 0
	v_mov_b32_e32 v151, 0
	v_mov_b32_e32 v160, 0
	v_mov_b32_e32 v161, 0
	v_mov_b32_e32 v162, 0
	v_mov_b32_e32 v163, 0
	v_mov_b32_e32 v164, 0
	v_mov_b32_e32 v165, 0
	v_mov_b32_e32 v166, 0
	v_mov_b32_e32 v167, 0
	v_mov_b32_e32 v21, v20
	ds_read_b128 v[80:83], v21 offset:5120
	ds_read_b128 v[84:87], v21 offset:5136
	ds_read_b128 v[88:91], v21 offset:7680
	ds_read_b128 v[92:95], v21 offset:7696
	s_cmp_eq_u32 s7, 0
	s_mov_b32 s7, 0x12000
	s_cbranch_scc0 .Ldiff_lead_s_loop
.Ldiff_lead_n_loop:
	s_mul_i32 s18, s17, 0x1800
	s_mov_b32 s19, s13
	v_lshl_add_u64 v[22:23], v[216:217], 0, s[18:19]
	global_load_dwordx4 v[188:191], v[22:23], off offset:512
	s_mul_i32 s18, s16, 0x1800
	s_add_u32 s18, s18, s95
	v_lshl_add_u64 v[24:25], v[216:217], 0, s[18:19]
	global_load_dwordx4 v[192:195], v[24:25], off offset:512
	s_mov_b32 s18, s16
	v_lshl_add_u64 v[26:27], v[218:219], 0, s[18:19]
	global_load_dwordx2 v[222:223], v[26:27], off
	global_load_dwordx2 v[220:221], v[26:27], off offset:64
	ds_read_b128 v[204:207], v18
	s_setprio 3
	s_waitcnt lgkmcnt(0)
	v_mfma_f32_32x32x64_f8f6f4 v[64:79], v[80:87], v[144:151], v[64:79] blgp:1
	v_mfma_f32_32x32x64_f8f6f4 v[96:111], v[80:87], v[160:167], v[96:111] blgp:1
	ds_read_b128 v[80:83], v18 offset:32
	ds_read_b128 v[84:87], v18 offset:64
	v_mfma_f32_32x32x64_f8f6f4 v[48:63], v[88:95], v[160:167], v[48:63] blgp:1
	v_mfma_f32_32x32x64_f8f6f4 v[32:47], v[88:95], v[144:151], v[32:47] blgp:1
	ds_read_b128 v[88:91], v18 offset:96
	ds_read_b128 v[92:95], v18 offset:4608
	v_mfma_f32_16x16x128_f8f6f4 v[196:199], v[2:9], v[160:167], v[196:199] blgp:1
	v_mfma_f32_16x16x128_f8f6f4 v[200:203], v[2:9], v[144:151], v[200:203] blgp:1
	v_mfma_f32_32x32x16_bf16 v[160:175], v[204:207], v[10:13], -4.0
	ds_read_b128 v[204:207], v18 offset:4640
	s_waitcnt lgkmcnt(3)
	v_mfma_f32_32x32x16_bf16 v[160:175], v[80:83], v[176:179], v[160:175]
	v_mfma_f32_32x32x16_bf16 v[144:159], v[84:87], v[180:183], -4.0
	ds_read_b128 v[80:83], v18 offset:4672
	ds_read_b128 v[84:87], v18 offset:4704
	s_waitcnt lgkmcnt(3)
	v_mfma_f32_32x32x16_bf16 v[144:159], v[88:91], v[184:187], v[144:159]
	v_mfma_f32_32x32x16_bf16 v[128:143], v[92:95], v[10:13], -4.0
	s_waitcnt lgkmcnt(0)
	v_mfma_f32_32x32x16_bf16 v[128:143], v[204:207], v[176:179], v[128:143]
	v_mfma_f32_32x32x16_bf16 v[112:127], v[80:83], v[180:183], -4.0
	v_mfma_f32_32x32x16_bf16 v[112:127], v[84:87], v[184:187], v[112:127]
	ds_read_b128 v[80:83], v20
	ds_read_b128 v[84:87], v20 offset:16
	ds_read_b128 v[88:91], v20 offset:2560
	ds_read_b128 v[92:95], v20 offset:2576
	ds_read_b128 v[204:207], v18 offset:9216
	s_setprio 0
	s_nop 1
	v_exp_f32_e32 v160, v160
	v_exp_f32_e32 v161, v161
	v_exp_f32_e32 v162, v162
	v_exp_f32_e32 v163, v163
	v_exp_f32_e32 v164, v164
	v_exp_f32_e32 v165, v165
	v_exp_f32_e32 v166, v166
	v_exp_f32_e32 v167, v167
	v_cvt_pkrtz_f16_f32 v160, v160, v161
	v_cvt_pkrtz_f16_f32 v161, v162, v163
	v_perm_b32 v160, v161, v160, s1
	v_exp_f32_e32 v168, v168
	v_exp_f32_e32 v169, v169
	v_exp_f32_e32 v170, v170
	v_exp_f32_e32 v171, v171
	v_cvt_pkrtz_f16_f32 v164, v164, v165
	v_cvt_pkrtz_f16_f32 v165, v166, v167
	v_perm_b32 v161, v165, v164, s1
	v_exp_f32_e32 v172, v172
	v_exp_f32_e32 v173, v173
	v_exp_f32_e32 v174, v174
	v_exp_f32_e32 v175, v175
	v_cvt_pkrtz_f16_f32 v168, v168, v169
	v_cvt_pkrtz_f16_f32 v169, v170, v171
	v_perm_b32 v162, v169, v168, s1
	v_exp_f32_e32 v144, v144
	v_exp_f32_e32 v145, v145
	v_exp_f32_e32 v146, v146
	v_exp_f32_e32 v147, v147
	v_cvt_pkrtz_f16_f32 v172, v172, v173
	v_cvt_pkrtz_f16_f32 v173, v174, v175
	v_perm_b32 v163, v173, v172, s1
	v_exp_f32_e32 v148, v148
	v_exp_f32_e32 v149, v149
	v_exp_f32_e32 v150, v150
	v_exp_f32_e32 v151, v151
	v_cvt_pkrtz_f16_f32 v144, v144, v145
	v_cvt_pkrtz_f16_f32 v145, v146, v147
	v_perm_b32 v144, v145, v144, s1
	v_exp_f32_e32 v152, v152
	v_exp_f32_e32 v153, v153
	v_exp_f32_e32 v154, v154
	v_exp_f32_e32 v155, v155
	v_cvt_pkrtz_f16_f32 v148, v148, v149
	v_cvt_pkrtz_f16_f32 v149, v150, v151
	v_perm_b32 v145, v149, v148, s1
	v_exp_f32_e32 v156, v156
	v_exp_f32_e32 v157, v157
	v_exp_f32_e32 v158, v158
	v_exp_f32_e32 v159, v159
	v_cvt_pkrtz_f16_f32 v152, v152, v153
	v_cvt_pkrtz_f16_f32 v153, v154, v155
	v_perm_b32 v146, v153, v152, s1
	v_exp_f32_e32 v128, v128
	v_exp_f32_e32 v129, v129
	v_exp_f32_e32 v130, v130
	v_exp_f32_e32 v131, v131
	v_cvt_pkrtz_f16_f32 v156, v156, v157
	v_cvt_pkrtz_f16_f32 v157, v158, v159
	v_perm_b32 v147, v157, v156, s1
	v_exp_f32_e32 v132, v132
	v_exp_f32_e32 v133, v133
	v_exp_f32_e32 v134, v134
	v_exp_f32_e32 v135, v135
; #define MFMA32(a, b, c) __builtin_amdgcn_mfma_f32_32x32x16_bf16((a), (b), (c), 0, 0, 0)
; DI float exp2_hw(float x) { return __builtin_amdgcn_exp2f(x); }
; DI void phase_diff(KP p, int layer, u16* sm) {
;     ...
;         for (int hf = 0; hf < 2; ++hf) {
;           const u16* Kt = Ks + buf * (2 * KS_BUF) + hf * KS_BUF;
;           const unsigned char* Vt = Vl + buf * (2 * VL_BUF) + hf * VL_BUF;
;           f32x16 Sc[2][2];
; #pragma unroll
;           for (int sub = 0; sub < 2; ++sub)
; #pragma unroll
;             for (int m = 0; m < 2; ++m) {
; #pragma unroll
;               for (int i = 0; i < 16; ++i) Sc[sub][m][i] = cneg[i];
; #pragma unroll
;               for (int s = 0; s < 2; ++s) {
;                 const bf16x8 kf = *(const bf16x8*)(Kt + (sub * 32 + r) * KS_STRIDE + m * 32 + s * 16 + 8 * hh);
;                 Sc[sub][m] = MFMA32(kf, qf[m][s], Sc[sub][m]);
;               }
;             }
;           v8i_t pf[2];
; #pragma unroll
;           for (int sub = 0; sub < 2; ++sub)
; #pragma unroll
;             for (int m = 0; m < 2; ++m)
; #pragma unroll
;               for (int g = 0; g < 4; ++g) {
;                 float pv[4];
; #pragma unroll
;                 for (int e = 0; e < 4; ++e) pv[e] = exp2_hw(SH ? (Sc[sub][m][4 * g + e] - mbnd[m]) : Sc[sub][m][4 * g + e]);
;                 const unsigned ha = __builtin_bit_cast(unsigned, __builtin_amdgcn_cvt_pkrtz(pv[0], pv[1]));
;                 const unsigned hb = __builtin_bit_cast(unsigned, __builtin_amdgcn_cvt_pkrtz(pv[2], pv[3]));
;                 pf[m][4 * sub + g] = (int)__builtin_amdgcn_perm(hb, ha, 0x07050301u);
;               }
; #pragma unroll
;           for (int mb = 0; mb < 2; ++mb) {
;             const v8i_t vf = *(const v8i_t*)(Vt + (mb * 32 + r) * VL_STRIDE + 32 * hh);
;             O[0][mb] = __builtin_amdgcn_mfma_scale_f32_32x32x64_f8f6f4(vf, pf[0], O[0][mb], 0, 1, 0, 0x7F7F7F7F, 0, 0x7F7F7F7F);
;             O[1][mb] = __builtin_amdgcn_mfma_scale_f32_32x32x64_f8f6f4(vf, pf[1], O[1][mb], 0, 1, 0, 0x7F7F7F7F, 0, 0x7F7F7F7F);
;           }
;           L4[0] = __builtin_amdgcn_mfma_scale_f32_16x16x128_f8f6f4(ones8, pf[0], L4[0], 0, 1, 0, 0x7F7F7F7F, 0, 0x7F7F7F7F);
;           L4[1] = __builtin_amdgcn_mfma_scale_f32_16x16x128_f8f6f4(ones8, pf[1], L4[1], 0, 1, 0, 0x7F7F7F7F, 0, 0x7F7F7F7F);
	v_cvt_pkrtz_f16_f32 v128, v128, v129
	v_cvt_pkrtz_f16_f32 v129, v130, v131
	v_perm_b32 v164, v129, v128, s1
	v_exp_f32_e32 v136, v136
	v_exp_f32_e32 v137, v137
	v_exp_f32_e32 v138, v138
	v_exp_f32_e32 v139, v139
	v_cvt_pkrtz_f16_f32 v132, v132, v133
	v_cvt_pkrtz_f16_f32 v133, v134, v135
	v_perm_b32 v165, v133, v132, s1
	v_exp_f32_e32 v140, v140
	v_exp_f32_e32 v141, v141
	v_exp_f32_e32 v142, v142
	v_exp_f32_e32 v143, v143
	v_cvt_pkrtz_f16_f32 v136, v136, v137
	v_cvt_pkrtz_f16_f32 v137, v138, v139
	v_perm_b32 v166, v137, v136, s1
	v_exp_f32_e32 v112, v112
	v_exp_f32_e32 v113, v113
	v_exp_f32_e32 v114, v114
	v_exp_f32_e32 v115, v115
	v_cvt_pkrtz_f16_f32 v140, v140, v141
	v_cvt_pkrtz_f16_f32 v141, v142, v143
	v_perm_b32 v167, v141, v140, s1
	v_exp_f32_e32 v116, v116
	v_exp_f32_e32 v117, v117
	v_exp_f32_e32 v118, v118
	v_exp_f32_e32 v119, v119
	v_cvt_pkrtz_f16_f32 v112, v112, v113
	v_cvt_pkrtz_f16_f32 v113, v114, v115
	v_perm_b32 v148, v113, v112, s1
	v_exp_f32_e32 v120, v120
	v_exp_f32_e32 v121, v121
	v_exp_f32_e32 v122, v122
	v_exp_f32_e32 v123, v123
	v_cvt_pkrtz_f16_f32 v116, v116, v117
	v_cvt_pkrtz_f16_f32 v117, v118, v119
	v_perm_b32 v149, v117, v116, s1
	v_exp_f32_e32 v124, v124
	v_exp_f32_e32 v125, v125
	v_exp_f32_e32 v126, v126
	v_exp_f32_e32 v127, v127
	v_cvt_pkrtz_f16_f32 v120, v120, v121
	v_cvt_pkrtz_f16_f32 v121, v122, v123
	v_perm_b32 v150, v121, v120, s1
	s_nop 0
	v_cvt_pkrtz_f16_f32 v124, v124, v125
	v_cvt_pkrtz_f16_f32 v125, v126, v127
	v_perm_b32 v151, v125, v124, s1
	s_setprio 3
	s_waitcnt lgkmcnt(0)
	v_mfma_f32_32x32x64_f8f6f4 v[64:79], v[80:87], v[144:151], v[64:79] blgp:1
	v_mfma_f32_32x32x64_f8f6f4 v[96:111], v[80:87], v[160:167], v[96:111] blgp:1
	ds_read_b128 v[80:83], v18 offset:9248
	ds_read_b128 v[84:87], v18 offset:9280
	v_mfma_f32_32x32x64_f8f6f4 v[48:63], v[88:95], v[160:167], v[48:63] blgp:1
	v_mfma_f32_32x32x64_f8f6f4 v[32:47], v[88:95], v[144:151], v[32:47] blgp:1
	ds_read_b128 v[88:91], v18 offset:9312
	ds_read_b128 v[92:95], v18 offset:13824
	v_mfma_f32_16x16x128_f8f6f4 v[196:199], v[2:9], v[160:167], v[196:199] blgp:1
	v_mfma_f32_16x16x128_f8f6f4 v[200:203], v[2:9], v[144:151], v[200:203] blgp:1
	v_mfma_f32_32x32x16_bf16 v[160:175], v[204:207], v[10:13], -4.0
	ds_read_b128 v[204:207], v18 offset:13856
	s_waitcnt lgkmcnt(3)
	v_mfma_f32_32x32x16_bf16 v[160:175], v[80:83], v[176:179], v[160:175]
	v_mfma_f32_32x32x16_bf16 v[144:159], v[84:87], v[180:183], -4.0
	ds_read_b128 v[80:83], v18 offset:13888
	ds_read_b128 v[84:87], v18 offset:13920
	s_waitcnt lgkmcnt(3)
	v_mfma_f32_32x32x16_bf16 v[144:159], v[88:91], v[184:187], v[144:159]
	v_mfma_f32_32x32x16_bf16 v[128:143], v[92:95], v[10:13], -4.0
	s_waitcnt lgkmcnt(0)
	v_mfma_f32_32x32x16_bf16 v[128:143], v[204:207], v[176:179], v[128:143]
	v_mfma_f32_32x32x16_bf16 v[112:127], v[80:83], v[180:183], -4.0
	v_mfma_f32_32x32x16_bf16 v[112:127], v[84:87], v[184:187], v[112:127]
	s_setprio 0
	s_nop 1
	v_exp_f32_e32 v160, v160
	v_exp_f32_e32 v161, v161
	v_exp_f32_e32 v162, v162
	v_exp_f32_e32 v163, v163
	v_exp_f32_e32 v164, v164
	v_exp_f32_e32 v165, v165
	v_exp_f32_e32 v166, v166
	v_exp_f32_e32 v167, v167
	v_cvt_pkrtz_f16_f32 v160, v160, v161
	v_cvt_pkrtz_f16_f32 v161, v162, v163
	v_perm_b32 v160, v161, v160, s1
	v_exp_f32_e32 v168, v168
	v_exp_f32_e32 v169, v169
	v_exp_f32_e32 v170, v170
	v_exp_f32_e32 v171, v171
	v_cvt_pkrtz_f16_f32 v164, v164, v165
	v_cvt_pkrtz_f16_f32 v165, v166, v167
	v_perm_b32 v161, v165, v164, s1
	v_exp_f32_e32 v172, v172
	v_exp_f32_e32 v173, v173
	v_exp_f32_e32 v174, v174
	v_exp_f32_e32 v175, v175
	v_cvt_pkrtz_f16_f32 v168, v168, v169
	v_cvt_pkrtz_f16_f32 v169, v170, v171
	v_perm_b32 v162, v169, v168, s1
	v_exp_f32_e32 v144, v144
	v_exp_f32_e32 v145, v145
	v_exp_f32_e32 v146, v146
	v_exp_f32_e32 v147, v147
	v_cvt_pkrtz_f16_f32 v172, v172, v173
	v_cvt_pkrtz_f16_f32 v173, v174, v175
	v_perm_b32 v163, v173, v172, s1
	v_exp_f32_e32 v148, v148
	v_exp_f32_e32 v149, v149
	v_exp_f32_e32 v150, v150
	v_exp_f32_e32 v151, v151
	v_cvt_pkrtz_f16_f32 v144, v144, v145
	v_cvt_pkrtz_f16_f32 v145, v146, v147
	v_perm_b32 v144, v145, v144, s1
	v_exp_f32_e32 v152, v152
	v_exp_f32_e32 v153, v153
	v_exp_f32_e32 v154, v154
	v_exp_f32_e32 v155, v155
	v_cvt_pkrtz_f16_f32 v148, v148, v149
	v_cvt_pkrtz_f16_f32 v149, v150, v151
	v_perm_b32 v145, v149, v148, s1
	v_exp_f32_e32 v156, v156
	v_exp_f32_e32 v157, v157
	v_exp_f32_e32 v158, v158
	v_exp_f32_e32 v159, v159
	v_cvt_pkrtz_f16_f32 v152, v152, v153
	v_cvt_pkrtz_f16_f32 v153, v154, v155
	v_perm_b32 v146, v153, v152, s1
	v_exp_f32_e32 v128, v128
	v_exp_f32_e32 v129, v129
	v_exp_f32_e32 v130, v130
	v_exp_f32_e32 v131, v131
	v_cvt_pkrtz_f16_f32 v156, v156, v157
	v_cvt_pkrtz_f16_f32 v157, v158, v159
	v_perm_b32 v147, v157, v156, s1
	v_exp_f32_e32 v132, v132
	v_exp_f32_e32 v133, v133
	v_exp_f32_e32 v134, v134
	v_exp_f32_e32 v135, v135
	v_cvt_pkrtz_f16_f32 v128, v128, v129
	v_cvt_pkrtz_f16_f32 v129, v130, v131
	v_perm_b32 v164, v129, v128, s1
	v_exp_f32_e32 v136, v136
	v_exp_f32_e32 v137, v137
	v_exp_f32_e32 v138, v138
	v_exp_f32_e32 v139, v139
	v_cvt_pkrtz_f16_f32 v132, v132, v133
	v_cvt_pkrtz_f16_f32 v133, v134, v135
	v_perm_b32 v165, v133, v132, s1
	v_exp_f32_e32 v140, v140
	v_exp_f32_e32 v141, v141
	v_exp_f32_e32 v142, v142
	v_exp_f32_e32 v143, v143
	v_cvt_pkrtz_f16_f32 v136, v136, v137
	v_cvt_pkrtz_f16_f32 v137, v138, v139
	v_perm_b32 v166, v137, v136, s1
	v_exp_f32_e32 v112, v112
	v_exp_f32_e32 v113, v113
	v_exp_f32_e32 v114, v114
	v_exp_f32_e32 v115, v115
	v_cvt_pkrtz_f16_f32 v140, v140, v141
	v_cvt_pkrtz_f16_f32 v141, v142, v143
	v_perm_b32 v167, v141, v140, s1
	v_exp_f32_e32 v116, v116
	v_exp_f32_e32 v117, v117
	v_exp_f32_e32 v118, v118
	v_exp_f32_e32 v119, v119
	v_cvt_pkrtz_f16_f32 v112, v112, v113
	v_cvt_pkrtz_f16_f32 v113, v114, v115
	v_perm_b32 v148, v113, v112, s1
	v_exp_f32_e32 v120, v120
	v_exp_f32_e32 v121, v121
	v_exp_f32_e32 v122, v122
	v_exp_f32_e32 v123, v123
	v_cvt_pkrtz_f16_f32 v116, v116, v117
	v_cvt_pkrtz_f16_f32 v117, v118, v119
	v_perm_b32 v149, v117, v116, s1
	v_exp_f32_e32 v124, v124
	v_exp_f32_e32 v125, v125
	v_exp_f32_e32 v126, v126
	v_exp_f32_e32 v127, v127
	v_cvt_pkrtz_f16_f32 v120, v120, v121
	v_cvt_pkrtz_f16_f32 v121, v122, v123
	v_perm_b32 v150, v121, v120, s1
	s_nop 0
	v_cvt_pkrtz_f16_f32 v124, v124, v125
	v_cvt_pkrtz_f16_f32 v125, v126, v127
	v_perm_b32 v151, v125, v124, s1
	s_waitcnt vmcnt(0)
; DI void phase_diff(KP p, int layer, u16* sm) {
;     ...
;     auto lstore = [&](int buf) __attribute__((always_inline)) {
;       u16* kd = Ks + buf * (2 * KS_BUF) + key0 * KS_STRIDE + ch * 8;
;       *(uint4*)kd = kra; *(uint4*)(kd + KS_BUF) = krb;
;       unsigned char* vd = Vl + buf * (2 * VL_BUF) + key0 * VL_STRIDE + 4 * ch;
;       *(unsigned*)vd = vra.x; *(unsigned*)(vd + 32) = vra.y;
;       *(unsigned*)(vd + VL_BUF) = vrb.x; *(unsigned*)(vd + VL_BUF + 32) = vrb.y;
;     };
;     gload(0); lstore(0);
;     __syncthreads();
;     if (w >= 4) __builtin_amdgcn_s_setprio(1);
;     auto tile_loop = [&](auto shifted) __attribute__((always_inline)) {
;       constexpr bool SH = decltype(shifted)::value;
;       for (int st = 0; st < 128; ++st) {
;         const int buf = st & 1;
;         gload(st + 1);
; #pragma unroll
;         for (int hf = 0; hf < 2; ++hf) {
;           const u16* Kt = Ks + buf * (2 * KS_BUF) + hf * KS_BUF;
;           const unsigned char* Vt = Vl + buf * (2 * VL_BUF) + hf * VL_BUF;
;           f32x16 Sc[2][2];
; #pragma unroll
;           for (int sub = 0; sub < 2; ++sub)
; #pragma unroll
;             for (int m = 0; m < 2; ++m) {
; #pragma unroll
;               for (int i = 0; i < 16; ++i) Sc[sub][m][i] = cneg[i];
; #pragma unroll
;               for (int s = 0; s < 2; ++s) {
;                 const bf16x8 kf = *(const bf16x8*)(Kt + (sub * 32 + r) * KS_STRIDE + m * 32 + s * 16 + 8 * hh);
;                 Sc[sub][m] = MFMA32(kf, qf[m][s], Sc[sub][m]);
;               }
;             }
;           v8i_t pf[2];
; #pragma unroll
;           for (int sub = 0; sub < 2; ++sub)
; #pragma unroll
;             for (int m = 0; m < 2; ++m)
; #pragma unroll
;               for (int g = 0; g < 4; ++g) {
;                 float pv[4];
; #pragma unroll
;                 for (int e = 0; e < 4; ++e) pv[e] = exp2_hw(SH ? (Sc[sub][m][4 * g + e] - mbnd[m]) : Sc[sub][m][4 * g + e]);
;                 const unsigned ha = __builtin_bit_cast(unsigned, __builtin_amdgcn_cvt_pkrtz(pv[0], pv[1]));
;                 const unsigned hb = __builtin_bit_cast(unsigned, __builtin_amdgcn_cvt_pkrtz(pv[2], pv[3]));
;                 pf[m][4 * sub + g] = (int)__builtin_amdgcn_perm(hb, ha, 0x07050301u);
;               }
; #pragma unroll
;           for (int mb = 0; mb < 2; ++mb) {
;             const v8i_t vf = *(const v8i_t*)(Vt + (mb * 32 + r) * VL_STRIDE + 32 * hh);
	v_add_u32_e32 v112, s99, v250
	ds_write_b128 v112, v[188:191]
	v_add_u32_e32 v113, s100, v250
	ds_write_b128 v113, v[192:195] offset:9216
	v_add_u32_e32 v114, s101, v251
	ds_write2_b32 v114, v222, v223 offset1:8
	v_add_u32_e32 v115, 0x1400, v114
	ds_write2_b32 v115, v220, v221 offset1:8
	v_mov_b32_e32 v21, v20
	s_mov_b32 s98, s100
	s_mov_b32 s100, s99
	s_add_i32 s99, s99, 0x4800
	s_cmp_eq_u32 s99, 0x12000
	s_cselect_b32 s99, 0, s99
	s_mov_b32 s7, s101
	s_add_i32 s101, s101, 0x2800
	s_cmp_eq_u32 s101, 0x1c000
	s_cselect_b32 s101, 0x12000, s101
	s_mov_b32 s16, s17
	s_add_i32 s17, s17, 0x80
	s_and_b32 s17, s17, 0x3fff
	v_add_u32_e32 v18, s98, v16
	v_add_u32_e32 v20, s7, v17
	ds_read_b128 v[80:83], v21 offset:5120
	ds_read_b128 v[84:87], v21 offset:5136
	ds_read_b128 v[88:91], v21 offset:7680
	ds_read_b128 v[92:95], v21 offset:7696
	s_add_i32 s6, s6, 1
	s_cmpk_lt_u32 s6, 0x80
	s_waitcnt lgkmcnt(0)
	s_barrier
	s_cbranch_scc1 .Ldiff_lead_n_loop
	s_setprio 3
	s_waitcnt lgkmcnt(0)
	v_mfma_f32_32x32x64_f8f6f4 v[64:79], v[80:87], v[144:151], v[64:79] blgp:1
	v_mfma_f32_32x32x64_f8f6f4 v[96:111], v[80:87], v[160:167], v[96:111] blgp:1
	v_mfma_f32_32x32x64_f8f6f4 v[48:63], v[88:95], v[160:167], v[48:63] blgp:1
	v_mfma_f32_32x32x64_f8f6f4 v[32:47], v[88:95], v[144:151], v[32:47] blgp:1
	v_mfma_f32_16x16x128_f8f6f4 v[196:199], v[2:9], v[160:167], v[196:199] blgp:1
	v_mfma_f32_16x16x128_f8f6f4 v[200:203], v[2:9], v[144:151], v[200:203] blgp:1
	v_mov_b32_e32 v16, -4.0
	v_mov_b32_e32 v17, -4.0
	v_mov_b32_e32 v18, -4.0
	v_mov_b32_e32 v19, -4.0
	v_mov_b32_e32 v20, -4.0
	v_mov_b32_e32 v21, -4.0
	v_mov_b32_e32 v22, -4.0
	v_mov_b32_e32 v23, -4.0
	v_mov_b32_e32 v24, -4.0
	v_mov_b32_e32 v25, -4.0
	v_mov_b32_e32 v26, -4.0
	v_mov_b32_e32 v27, -4.0
	s_nop 7
	s_branch .LBB0_462
.Ldiff_lead_s_loop:
	s_mul_i32 s18, s17, 0x1800
	s_mov_b32 s19, s13
	v_lshl_add_u64 v[22:23], v[216:217], 0, s[18:19]
	global_load_dwordx4 v[188:191], v[22:23], off offset:512
	s_mul_i32 s18, s16, 0x1800
	s_add_u32 s18, s18, s95
	v_lshl_add_u64 v[24:25], v[216:217], 0, s[18:19]
	global_load_dwordx4 v[192:195], v[24:25], off offset:512
	s_mov_b32 s18, s16
	v_lshl_add_u64 v[26:27], v[218:219], 0, s[18:19]
	global_load_dwordx2 v[222:223], v[26:27], off
	global_load_dwordx2 v[220:221], v[26:27], off offset:64
	ds_read_b128 v[204:207], v18
	s_setprio 3
	s_waitcnt lgkmcnt(0)
	v_mfma_f32_32x32x64_f8f6f4 v[64:79], v[80:87], v[144:151], v[64:79] blgp:1
	v_mfma_f32_32x32x64_f8f6f4 v[96:111], v[80:87], v[160:167], v[96:111] blgp:1
	ds_read_b128 v[80:83], v18 offset:32
	ds_read_b128 v[84:87], v18 offset:64
	v_mfma_f32_32x32x64_f8f6f4 v[48:63], v[88:95], v[160:167], v[48:63] blgp:1
	v_mfma_f32_32x32x64_f8f6f4 v[32:47], v[88:95], v[144:151], v[32:47] blgp:1
	ds_read_b128 v[88:91], v18 offset:96
	ds_read_b128 v[92:95], v18 offset:4608
	v_mfma_f32_16x16x128_f8f6f4 v[196:199], v[2:9], v[160:167], v[196:199] blgp:1
	v_mfma_f32_16x16x128_f8f6f4 v[200:203], v[2:9], v[144:151], v[200:203] blgp:1
	v_mfma_f32_32x32x16_bf16 v[160:175], v[204:207], v[10:13], -4.0
	ds_read_b128 v[204:207], v18 offset:4640
	s_waitcnt lgkmcnt(3)
	v_mfma_f32_32x32x16_bf16 v[160:175], v[80:83], v[176:179], v[160:175]
	v_mfma_f32_32x32x16_bf16 v[144:159], v[84:87], v[180:183], -4.0
	ds_read_b128 v[80:83], v18 offset:4672
	ds_read_b128 v[84:87], v18 offset:4704
	s_waitcnt lgkmcnt(3)
	v_mfma_f32_32x32x16_bf16 v[144:159], v[88:91], v[184:187], v[144:159]
	v_mfma_f32_32x32x16_bf16 v[128:143], v[92:95], v[10:13], -4.0
	s_waitcnt lgkmcnt(0)
	v_mfma_f32_32x32x16_bf16 v[128:143], v[204:207], v[176:179], v[128:143]
	v_mfma_f32_32x32x16_bf16 v[112:127], v[80:83], v[180:183], -4.0
	v_mfma_f32_32x32x16_bf16 v[112:127], v[84:87], v[184:187], v[112:127]
	ds_read_b128 v[80:83], v20
	ds_read_b128 v[84:87], v20 offset:16
	ds_read_b128 v[88:91], v20 offset:2560
	ds_read_b128 v[92:95], v20 offset:2576
	ds_read_b128 v[204:207], v18 offset:9216
	s_setprio 0
	s_nop 1
	v_sub_f32_e32 v160, v160, v213
	v_sub_f32_e32 v161, v161, v213
	v_sub_f32_e32 v162, v162, v213
	v_sub_f32_e32 v163, v163, v213
	v_exp_f32_e32 v160, v160
	v_exp_f32_e32 v161, v161
	v_exp_f32_e32 v162, v162
	v_exp_f32_e32 v163, v163
	v_sub_f32_e32 v164, v164, v213
	v_sub_f32_e32 v165, v165, v213
	v_sub_f32_e32 v166, v166, v213
	v_sub_f32_e32 v167, v167, v213
	v_exp_f32_e32 v164, v164
	v_exp_f32_e32 v165, v165
	v_exp_f32_e32 v166, v166
	v_exp_f32_e32 v167, v167
	v_cvt_pkrtz_f16_f32 v160, v160, v161
	v_cvt_pkrtz_f16_f32 v161, v162, v163
	v_perm_b32 v160, v161, v160, s1
	v_sub_f32_e32 v168, v168, v213
	v_sub_f32_e32 v169, v169, v213
	v_sub_f32_e32 v170, v170, v213
	v_sub_f32_e32 v171, v171, v213
	v_exp_f32_e32 v168, v168
	v_exp_f32_e32 v169, v169
	v_exp_f32_e32 v170, v170
	v_exp_f32_e32 v171, v171
	v_cvt_pkrtz_f16_f32 v164, v164, v165
	v_cvt_pkrtz_f16_f32 v165, v166, v167
	v_perm_b32 v161, v165, v164, s1
	v_sub_f32_e32 v172, v172, v213
	v_sub_f32_e32 v173, v173, v213
	v_sub_f32_e32 v174, v174, v213
	v_sub_f32_e32 v175, v175, v213
	v_exp_f32_e32 v172, v172
	v_exp_f32_e32 v173, v173
	v_exp_f32_e32 v174, v174
	v_exp_f32_e32 v175, v175
	v_cvt_pkrtz_f16_f32 v168, v168, v169
	v_cvt_pkrtz_f16_f32 v169, v170, v171
	v_perm_b32 v162, v169, v168, s1
	v_sub_f32_e32 v144, v144, v237
	v_sub_f32_e32 v145, v145, v237
	v_sub_f32_e32 v146, v146, v237
	v_sub_f32_e32 v147, v147, v237
	v_exp_f32_e32 v144, v144
	v_exp_f32_e32 v145, v145
	v_exp_f32_e32 v146, v146
	v_exp_f32_e32 v147, v147
	v_cvt_pkrtz_f16_f32 v172, v172, v173
	v_cvt_pkrtz_f16_f32 v173, v174, v175
	v_perm_b32 v163, v173, v172, s1
	v_sub_f32_e32 v148, v148, v237
	v_sub_f32_e32 v149, v149, v237
	v_sub_f32_e32 v150, v150, v237
	v_sub_f32_e32 v151, v151, v237
; #define MFMA32(a, b, c) __builtin_amdgcn_mfma_f32_32x32x16_bf16((a), (b), (c), 0, 0, 0)
; DI float exp2_hw(float x) { return __builtin_amdgcn_exp2f(x); }
; DI void phase_diff(KP p, int layer, u16* sm) {
;     ...
;           f32x16 Sc[2][2];
; #pragma unroll
;           for (int sub = 0; sub < 2; ++sub)
; #pragma unroll
;             for (int m = 0; m < 2; ++m) {
; #pragma unroll
;               for (int i = 0; i < 16; ++i) Sc[sub][m][i] = cneg[i];
; #pragma unroll
;               for (int s = 0; s < 2; ++s) {
;                 const bf16x8 kf = *(const bf16x8*)(Kt + (sub * 32 + r) * KS_STRIDE + m * 32 + s * 16 + 8 * hh);
;                 Sc[sub][m] = MFMA32(kf, qf[m][s], Sc[sub][m]);
;               }
;             }
;           v8i_t pf[2];
; #pragma unroll
;           for (int sub = 0; sub < 2; ++sub)
; #pragma unroll
;             for (int m = 0; m < 2; ++m)
; #pragma unroll
;               for (int g = 0; g < 4; ++g) {
;                 float pv[4];
; #pragma unroll
;                 for (int e = 0; e < 4; ++e) pv[e] = exp2_hw(SH ? (Sc[sub][m][4 * g + e] - mbnd[m]) : Sc[sub][m][4 * g + e]);
;                 const unsigned ha = __builtin_bit_cast(unsigned, __builtin_amdgcn_cvt_pkrtz(pv[0], pv[1]));
;                 const unsigned hb = __builtin_bit_cast(unsigned, __builtin_amdgcn_cvt_pkrtz(pv[2], pv[3]));
;                 pf[m][4 * sub + g] = (int)__builtin_amdgcn_perm(hb, ha, 0x07050301u);
;               }
; #pragma unroll
;           for (int mb = 0; mb < 2; ++mb) {
;             const v8i_t vf = *(const v8i_t*)(Vt + (mb * 32 + r) * VL_STRIDE + 32 * hh);
;             O[0][mb] = __builtin_amdgcn_mfma_scale_f32_32x32x64_f8f6f4(vf, pf[0], O[0][mb], 0, 1, 0, 0x7F7F7F7F, 0, 0x7F7F7F7F);
;             O[1][mb] = __builtin_amdgcn_mfma_scale_f32_32x32x64_f8f6f4(vf, pf[1], O[1][mb], 0, 1, 0, 0x7F7F7F7F, 0, 0x7F7F7F7F);
;           }
;           L4[0] = __builtin_amdgcn_mfma_scale_f32_16x16x128_f8f6f4(ones8, pf[0], L4[0], 0, 1, 0, 0x7F7F7F7F, 0, 0x7F7F7F7F);
;           L4[1] = __builtin_amdgcn_mfma_scale_f32_16x16x128_f8f6f4(ones8, pf[1], L4[1], 0, 1, 0, 0x7F7F7F7F, 0, 0x7F7F7F7F);
	v_exp_f32_e32 v148, v148
	v_exp_f32_e32 v149, v149
	v_exp_f32_e32 v150, v150
	v_exp_f32_e32 v151, v151
	v_cvt_pkrtz_f16_f32 v144, v144, v145
	v_cvt_pkrtz_f16_f32 v145, v146, v147
	v_perm_b32 v144, v145, v144, s1
	v_sub_f32_e32 v152, v152, v237
	v_sub_f32_e32 v153, v153, v237
	v_sub_f32_e32 v154, v154, v237
	v_sub_f32_e32 v155, v155, v237
	v_exp_f32_e32 v152, v152
	v_exp_f32_e32 v153, v153
	v_exp_f32_e32 v154, v154
	v_exp_f32_e32 v155, v155
	v_cvt_pkrtz_f16_f32 v148, v148, v149
	v_cvt_pkrtz_f16_f32 v149, v150, v151
	v_perm_b32 v145, v149, v148, s1
	v_sub_f32_e32 v156, v156, v237
	v_sub_f32_e32 v157, v157, v237
	v_sub_f32_e32 v158, v158, v237
	v_sub_f32_e32 v159, v159, v237
	v_exp_f32_e32 v156, v156
	v_exp_f32_e32 v157, v157
	v_exp_f32_e32 v158, v158
	v_exp_f32_e32 v159, v159
	v_cvt_pkrtz_f16_f32 v152, v152, v153
	v_cvt_pkrtz_f16_f32 v153, v154, v155
	v_perm_b32 v146, v153, v152, s1
	v_sub_f32_e32 v128, v128, v213
	v_sub_f32_e32 v129, v129, v213
	v_sub_f32_e32 v130, v130, v213
	v_sub_f32_e32 v131, v131, v213
	v_exp_f32_e32 v128, v128
	v_exp_f32_e32 v129, v129
	v_exp_f32_e32 v130, v130
	v_exp_f32_e32 v131, v131
	v_cvt_pkrtz_f16_f32 v156, v156, v157
	v_cvt_pkrtz_f16_f32 v157, v158, v159
	v_perm_b32 v147, v157, v156, s1
	v_sub_f32_e32 v132, v132, v213
	v_sub_f32_e32 v133, v133, v213
	v_sub_f32_e32 v134, v134, v213
	v_sub_f32_e32 v135, v135, v213
	v_exp_f32_e32 v132, v132
	v_exp_f32_e32 v133, v133
	v_exp_f32_e32 v134, v134
	v_exp_f32_e32 v135, v135
	v_cvt_pkrtz_f16_f32 v128, v128, v129
	v_cvt_pkrtz_f16_f32 v129, v130, v131
	v_perm_b32 v164, v129, v128, s1
	v_sub_f32_e32 v136, v136, v213
	v_sub_f32_e32 v137, v137, v213
	v_sub_f32_e32 v138, v138, v213
	v_sub_f32_e32 v139, v139, v213
	v_exp_f32_e32 v136, v136
	v_exp_f32_e32 v137, v137
	v_exp_f32_e32 v138, v138
	v_exp_f32_e32 v139, v139
	v_cvt_pkrtz_f16_f32 v132, v132, v133
	v_cvt_pkrtz_f16_f32 v133, v134, v135
	v_perm_b32 v165, v133, v132, s1
	v_sub_f32_e32 v140, v140, v213
	v_sub_f32_e32 v141, v141, v213
	v_sub_f32_e32 v142, v142, v213
	v_sub_f32_e32 v143, v143, v213
	v_exp_f32_e32 v140, v140
	v_exp_f32_e32 v141, v141
	v_exp_f32_e32 v142, v142
	v_exp_f32_e32 v143, v143
	v_cvt_pkrtz_f16_f32 v136, v136, v137
	v_cvt_pkrtz_f16_f32 v137, v138, v139
	v_perm_b32 v166, v137, v136, s1
	v_sub_f32_e32 v112, v112, v237
	v_sub_f32_e32 v113, v113, v237
	v_sub_f32_e32 v114, v114, v237
	v_sub_f32_e32 v115, v115, v237
	v_exp_f32_e32 v112, v112
	v_exp_f32_e32 v113, v113
	v_exp_f32_e32 v114, v114
	v_exp_f32_e32 v115, v115
	v_cvt_pkrtz_f16_f32 v140, v140, v141
	v_cvt_pkrtz_f16_f32 v141, v142, v143
	v_perm_b32 v167, v141, v140, s1
	v_sub_f32_e32 v116, v116, v237
	v_sub_f32_e32 v117, v117, v237
	v_sub_f32_e32 v118, v118, v237
	v_sub_f32_e32 v119, v119, v237
	v_exp_f32_e32 v116, v116
	v_exp_f32_e32 v117, v117
	v_exp_f32_e32 v118, v118
	v_exp_f32_e32 v119, v119
	v_cvt_pkrtz_f16_f32 v112, v112, v113
	v_cvt_pkrtz_f16_f32 v113, v114, v115
	v_perm_b32 v148, v113, v112, s1
	v_sub_f32_e32 v120, v120, v237
	v_sub_f32_e32 v121, v121, v237
	v_sub_f32_e32 v122, v122, v237
	v_sub_f32_e32 v123, v123, v237
	v_exp_f32_e32 v120, v120
	v_exp_f32_e32 v121, v121
	v_exp_f32_e32 v122, v122
	v_exp_f32_e32 v123, v123
	v_cvt_pkrtz_f16_f32 v116, v116, v117
	v_cvt_pkrtz_f16_f32 v117, v118, v119
	v_perm_b32 v149, v117, v116, s1
	v_sub_f32_e32 v124, v124, v237
	v_sub_f32_e32 v125, v125, v237
	v_sub_f32_e32 v126, v126, v237
	v_sub_f32_e32 v127, v127, v237
	v_exp_f32_e32 v124, v124
	v_exp_f32_e32 v125, v125
	v_exp_f32_e32 v126, v126
	v_exp_f32_e32 v127, v127
	v_cvt_pkrtz_f16_f32 v120, v120, v121
	v_cvt_pkrtz_f16_f32 v121, v122, v123
	v_perm_b32 v150, v121, v120, s1
	s_nop 0
	v_cvt_pkrtz_f16_f32 v124, v124, v125
	v_cvt_pkrtz_f16_f32 v125, v126, v127
	v_perm_b32 v151, v125, v124, s1
	s_setprio 3
	s_waitcnt lgkmcnt(0)
	v_mfma_f32_32x32x64_f8f6f4 v[64:79], v[80:87], v[144:151], v[64:79] blgp:1
	v_mfma_f32_32x32x64_f8f6f4 v[96:111], v[80:87], v[160:167], v[96:111] blgp:1
	ds_read_b128 v[80:83], v18 offset:9248
	ds_read_b128 v[84:87], v18 offset:9280
	v_mfma_f32_32x32x64_f8f6f4 v[48:63], v[88:95], v[160:167], v[48:63] blgp:1
	v_mfma_f32_32x32x64_f8f6f4 v[32:47], v[88:95], v[144:151], v[32:47] blgp:1
	ds_read_b128 v[88:91], v18 offset:9312
	ds_read_b128 v[92:95], v18 offset:13824
	v_mfma_f32_16x16x128_f8f6f4 v[196:199], v[2:9], v[160:167], v[196:199] blgp:1
	v_mfma_f32_16x16x128_f8f6f4 v[200:203], v[2:9], v[144:151], v[200:203] blgp:1
	v_mfma_f32_32x32x16_bf16 v[160:175], v[204:207], v[10:13], -4.0
	ds_read_b128 v[204:207], v18 offset:13856
	s_waitcnt lgkmcnt(3)
	v_mfma_f32_32x32x16_bf16 v[160:175], v[80:83], v[176:179], v[160:175]
	v_mfma_f32_32x32x16_bf16 v[144:159], v[84:87], v[180:183], -4.0
	ds_read_b128 v[80:83], v18 offset:13888
	ds_read_b128 v[84:87], v18 offset:13920
	s_waitcnt lgkmcnt(3)
	v_mfma_f32_32x32x16_bf16 v[144:159], v[88:91], v[184:187], v[144:159]
	v_mfma_f32_32x32x16_bf16 v[128:143], v[92:95], v[10:13], -4.0
	s_waitcnt lgkmcnt(0)
; DI void phase_diff(KP p, int layer, u16* sm) {
;     ...
;     auto lstore = [&](int buf) __attribute__((always_inline)) {
;       u16* kd = Ks + buf * (2 * KS_BUF) + key0 * KS_STRIDE + ch * 8;
;       *(uint4*)kd = kra; *(uint4*)(kd + KS_BUF) = krb;
;       unsigned char* vd = Vl + buf * (2 * VL_BUF) + key0 * VL_STRIDE + 4 * ch;
;       *(unsigned*)vd = vra.x; *(unsigned*)(vd + 32) = vra.y;
;       *(unsigned*)(vd + VL_BUF) = vrb.x; *(unsigned*)(vd + VL_BUF + 32) = vrb.y;
;     };
;     gload(0); lstore(0);
;     __syncthreads();
;     if (w >= 4) __builtin_amdgcn_s_setprio(1);
;     auto tile_loop = [&](auto shifted) __attribute__((always_inline)) {
;       constexpr bool SH = decltype(shifted)::value;
;       for (int st = 0; st < 128; ++st) {
;         const int buf = st & 1;
;         gload(st + 1);
; #pragma unroll
;         for (int hf = 0; hf < 2; ++hf) {
;           const u16* Kt = Ks + buf * (2 * KS_BUF) + hf * KS_BUF;
;           const unsigned char* Vt = Vl + buf * (2 * VL_BUF) + hf * VL_BUF;
;           f32x16 Sc[2][2];
; #pragma unroll
;           for (int sub = 0; sub < 2; ++sub)
; #pragma unroll
;             for (int m = 0; m < 2; ++m) {
; #pragma unroll
;               for (int i = 0; i < 16; ++i) Sc[sub][m][i] = cneg[i];
; #pragma unroll
;               for (int s = 0; s < 2; ++s) {
;                 const bf16x8 kf = *(const bf16x8*)(Kt + (sub * 32 + r) * KS_STRIDE + m * 32 + s * 16 + 8 * hh);
;                 Sc[sub][m] = MFMA32(kf, qf[m][s], Sc[sub][m]);
;               }
;             }
;           v8i_t pf[2];
; #pragma unroll
;           for (int sub = 0; sub < 2; ++sub)
; #pragma unroll
;             for (int m = 0; m < 2; ++m)
; #pragma unroll
;               for (int g = 0; g < 4; ++g) {
;                 float pv[4];
; #pragma unroll
;                 for (int e = 0; e < 4; ++e) pv[e] = exp2_hw(SH ? (Sc[sub][m][4 * g + e] - mbnd[m]) : Sc[sub][m][4 * g + e]);
;                 const unsigned ha = __builtin_bit_cast(unsigned, __builtin_amdgcn_cvt_pkrtz(pv[0], pv[1]));
;                 const unsigned hb = __builtin_bit_cast(unsigned, __builtin_amdgcn_cvt_pkrtz(pv[2], pv[3]));
;                 pf[m][4 * sub + g] = (int)__builtin_amdgcn_perm(hb, ha, 0x07050301u);
;               }
; #pragma unroll
;           for (int mb = 0; mb < 2; ++mb) {
;             const v8i_t vf = *(const v8i_t*)(Vt + (mb * 32 + r) * VL_STRIDE + 32 * hh);
	v_mfma_f32_32x32x16_bf16 v[128:143], v[204:207], v[176:179], v[128:143]
	v_mfma_f32_32x32x16_bf16 v[112:127], v[80:83], v[180:183], -4.0
	v_mfma_f32_32x32x16_bf16 v[112:127], v[84:87], v[184:187], v[112:127]
	s_setprio 0
	s_nop 1
	v_sub_f32_e32 v160, v160, v213
	v_sub_f32_e32 v161, v161, v213
	v_sub_f32_e32 v162, v162, v213
	v_sub_f32_e32 v163, v163, v213
	v_exp_f32_e32 v160, v160
	v_exp_f32_e32 v161, v161
	v_exp_f32_e32 v162, v162
	v_exp_f32_e32 v163, v163
	v_sub_f32_e32 v164, v164, v213
	v_sub_f32_e32 v165, v165, v213
	v_sub_f32_e32 v166, v166, v213
	v_sub_f32_e32 v167, v167, v213
	v_exp_f32_e32 v164, v164
	v_exp_f32_e32 v165, v165
	v_exp_f32_e32 v166, v166
	v_exp_f32_e32 v167, v167
	v_cvt_pkrtz_f16_f32 v160, v160, v161
	v_cvt_pkrtz_f16_f32 v161, v162, v163
	v_perm_b32 v160, v161, v160, s1
	v_sub_f32_e32 v168, v168, v213
	v_sub_f32_e32 v169, v169, v213
	v_sub_f32_e32 v170, v170, v213
	v_sub_f32_e32 v171, v171, v213
	v_exp_f32_e32 v168, v168
	v_exp_f32_e32 v169, v169
	v_exp_f32_e32 v170, v170
	v_exp_f32_e32 v171, v171
	v_cvt_pkrtz_f16_f32 v164, v164, v165
	v_cvt_pkrtz_f16_f32 v165, v166, v167
	v_perm_b32 v161, v165, v164, s1
	v_sub_f32_e32 v172, v172, v213
	v_sub_f32_e32 v173, v173, v213
	v_sub_f32_e32 v174, v174, v213
	v_sub_f32_e32 v175, v175, v213
	v_exp_f32_e32 v172, v172
	v_exp_f32_e32 v173, v173
	v_exp_f32_e32 v174, v174
	v_exp_f32_e32 v175, v175
	v_cvt_pkrtz_f16_f32 v168, v168, v169
	v_cvt_pkrtz_f16_f32 v169, v170, v171
	v_perm_b32 v162, v169, v168, s1
	v_sub_f32_e32 v144, v144, v237
	v_sub_f32_e32 v145, v145, v237
	v_sub_f32_e32 v146, v146, v237
	v_sub_f32_e32 v147, v147, v237
	v_exp_f32_e32 v144, v144
	v_exp_f32_e32 v145, v145
	v_exp_f32_e32 v146, v146
	v_exp_f32_e32 v147, v147
	v_cvt_pkrtz_f16_f32 v172, v172, v173
	v_cvt_pkrtz_f16_f32 v173, v174, v175
	v_perm_b32 v163, v173, v172, s1
	v_sub_f32_e32 v148, v148, v237
	v_sub_f32_e32 v149, v149, v237
	v_sub_f32_e32 v150, v150, v237
	v_sub_f32_e32 v151, v151, v237
	v_exp_f32_e32 v148, v148
	v_exp_f32_e32 v149, v149
	v_exp_f32_e32 v150, v150
	v_exp_f32_e32 v151, v151
	v_cvt_pkrtz_f16_f32 v144, v144, v145
	v_cvt_pkrtz_f16_f32 v145, v146, v147
	v_perm_b32 v144, v145, v144, s1
	v_sub_f32_e32 v152, v152, v237
	v_sub_f32_e32 v153, v153, v237
	v_sub_f32_e32 v154, v154, v237
	v_sub_f32_e32 v155, v155, v237
	v_exp_f32_e32 v152, v152
	v_exp_f32_e32 v153, v153
	v_exp_f32_e32 v154, v154
	v_exp_f32_e32 v155, v155
	v_cvt_pkrtz_f16_f32 v148, v148, v149
	v_cvt_pkrtz_f16_f32 v149, v150, v151
	v_perm_b32 v145, v149, v148, s1
	v_sub_f32_e32 v156, v156, v237
	v_sub_f32_e32 v157, v157, v237
	v_sub_f32_e32 v158, v158, v237
	v_sub_f32_e32 v159, v159, v237
	v_exp_f32_e32 v156, v156
	v_exp_f32_e32 v157, v157
	v_exp_f32_e32 v158, v158
	v_exp_f32_e32 v159, v159
	v_cvt_pkrtz_f16_f32 v152, v152, v153
	v_cvt_pkrtz_f16_f32 v153, v154, v155
	v_perm_b32 v146, v153, v152, s1
	v_sub_f32_e32 v128, v128, v213
	v_sub_f32_e32 v129, v129, v213
	v_sub_f32_e32 v130, v130, v213
	v_sub_f32_e32 v131, v131, v213
	v_exp_f32_e32 v128, v128
	v_exp_f32_e32 v129, v129
	v_exp_f32_e32 v130, v130
	v_exp_f32_e32 v131, v131
	v_cvt_pkrtz_f16_f32 v156, v156, v157
	v_cvt_pkrtz_f16_f32 v157, v158, v159
	v_perm_b32 v147, v157, v156, s1
	v_sub_f32_e32 v132, v132, v213
	v_sub_f32_e32 v133, v133, v213
	v_sub_f32_e32 v134, v134, v213
	v_sub_f32_e32 v135, v135, v213
	v_exp_f32_e32 v132, v132
	v_exp_f32_e32 v133, v133
	v_exp_f32_e32 v134, v134
	v_exp_f32_e32 v135, v135
	v_cvt_pkrtz_f16_f32 v128, v128, v129
	v_cvt_pkrtz_f16_f32 v129, v130, v131
	v_perm_b32 v164, v129, v128, s1
	v_sub_f32_e32 v136, v136, v213
	v_sub_f32_e32 v137, v137, v213
	v_sub_f32_e32 v138, v138, v213
	v_sub_f32_e32 v139, v139, v213
	v_exp_f32_e32 v136, v136
	v_exp_f32_e32 v137, v137
	v_exp_f32_e32 v138, v138
	v_exp_f32_e32 v139, v139
	v_cvt_pkrtz_f16_f32 v132, v132, v133
	v_cvt_pkrtz_f16_f32 v133, v134, v135
	v_perm_b32 v165, v133, v132, s1
	v_sub_f32_e32 v140, v140, v213
	v_sub_f32_e32 v141, v141, v213
	v_sub_f32_e32 v142, v142, v213
	v_sub_f32_e32 v143, v143, v213
	v_exp_f32_e32 v140, v140
	v_exp_f32_e32 v141, v141
	v_exp_f32_e32 v142, v142
	v_exp_f32_e32 v143, v143
	v_cvt_pkrtz_f16_f32 v136, v136, v137
	v_cvt_pkrtz_f16_f32 v137, v138, v139
	v_perm_b32 v166, v137, v136, s1
	v_sub_f32_e32 v112, v112, v237
	v_sub_f32_e32 v113, v113, v237
	v_sub_f32_e32 v114, v114, v237
	v_sub_f32_e32 v115, v115, v237
	v_exp_f32_e32 v112, v112
	v_exp_f32_e32 v113, v113
	v_exp_f32_e32 v114, v114
	v_exp_f32_e32 v115, v115
	v_cvt_pkrtz_f16_f32 v140, v140, v141
	v_cvt_pkrtz_f16_f32 v141, v142, v143
	v_perm_b32 v167, v141, v140, s1
	v_sub_f32_e32 v116, v116, v237
	v_sub_f32_e32 v117, v117, v237
	v_sub_f32_e32 v118, v118, v237
	v_sub_f32_e32 v119, v119, v237
	v_exp_f32_e32 v116, v116
	v_exp_f32_e32 v117, v117
	v_exp_f32_e32 v118, v118
	v_exp_f32_e32 v119, v119
	v_cvt_pkrtz_f16_f32 v112, v112, v113
	v_cvt_pkrtz_f16_f32 v113, v114, v115
	v_perm_b32 v148, v113, v112, s1
	v_sub_f32_e32 v120, v120, v237
	v_sub_f32_e32 v121, v121, v237
	v_sub_f32_e32 v122, v122, v237
	v_sub_f32_e32 v123, v123, v237
	v_exp_f32_e32 v120, v120
	v_exp_f32_e32 v121, v121
	v_exp_f32_e32 v122, v122
	v_exp_f32_e32 v123, v123
	v_cvt_pkrtz_f16_f32 v116, v116, v117
	v_cvt_pkrtz_f16_f32 v117, v118, v119
	v_perm_b32 v149, v117, v116, s1
	v_sub_f32_e32 v124, v124, v237
	v_sub_f32_e32 v125, v125, v237
	v_sub_f32_e32 v126, v126, v237
	v_sub_f32_e32 v127, v127, v237
	v_exp_f32_e32 v124, v124
	v_exp_f32_e32 v125, v125
	v_exp_f32_e32 v126, v126
	v_exp_f32_e32 v127, v127
	v_cvt_pkrtz_f16_f32 v120, v120, v121
	v_cvt_pkrtz_f16_f32 v121, v122, v123
	v_perm_b32 v150, v121, v120, s1
	s_nop 0
	v_cvt_pkrtz_f16_f32 v124, v124, v125
	v_cvt_pkrtz_f16_f32 v125, v126, v127
	v_perm_b32 v151, v125, v124, s1
	s_waitcnt vmcnt(0)
	v_add_u32_e32 v112, s99, v250
	ds_write_b128 v112, v[188:191]
	v_add_u32_e32 v113, s100, v250
	ds_write_b128 v113, v[192:195] offset:9216
	v_add_u32_e32 v114, s101, v251
	ds_write2_b32 v114, v222, v223 offset1:8
	v_add_u32_e32 v115, 0x1400, v114
	ds_write2_b32 v115, v220, v221 offset1:8
	v_mov_b32_e32 v21, v20
	s_mov_b32 s98, s100
	s_mov_b32 s100, s99
	s_add_i32 s99, s99, 0x4800
	s_cmp_eq_u32 s99, 0x12000
	s_cselect_b32 s99, 0, s99
	s_mov_b32 s7, s101
	s_add_i32 s101, s101, 0x2800
	s_cmp_eq_u32 s101, 0x1c000
	s_cselect_b32 s101, 0x12000, s101
	s_mov_b32 s16, s17
	s_add_i32 s17, s17, 0x80
	s_and_b32 s17, s17, 0x3fff
	v_add_u32_e32 v18, s98, v16
	v_add_u32_e32 v20, s7, v17
	ds_read_b128 v[80:83], v21 offset:5120
	ds_read_b128 v[84:87], v21 offset:5136
	ds_read_b128 v[88:91], v21 offset:7680
	ds_read_b128 v[92:95], v21 offset:7696
	s_add_i32 s6, s6, 1
	s_cmpk_lt_u32 s6, 0x80
	s_waitcnt lgkmcnt(0)
	s_barrier
; DI void phase_diff(KP p, int layer, u16* sm) {
;     ...
;     auto tile_loop = [&](auto shifted) __attribute__((always_inline)) {
;       constexpr bool SH = decltype(shifted)::value;
;       for (int st = 0; st < 128; ++st) {
;         const int buf = st & 1;
;         gload(st + 1);
; #pragma unroll
;         for (int hf = 0; hf < 2; ++hf) {
;           const u16* Kt = Ks + buf * (2 * KS_BUF) + hf * KS_BUF;
;           const unsigned char* Vt = Vl + buf * (2 * VL_BUF) + hf * VL_BUF;
;           f32x16 Sc[2][2];
; #pragma unroll
;           for (int sub = 0; sub < 2; ++sub)
; #pragma unroll
;             for (int m = 0; m < 2; ++m) {
; #pragma unroll
;               for (int i = 0; i < 16; ++i) Sc[sub][m][i] = cneg[i];
; #pragma unroll
;               for (int s = 0; s < 2; ++s) {
;                 const bf16x8 kf = *(const bf16x8*)(Kt + (sub * 32 + r) * KS_STRIDE + m * 32 + s * 16 + 8 * hh);
;                 Sc[sub][m] = MFMA32(kf, qf[m][s], Sc[sub][m]);
;               }
;             }
;           v8i_t pf[2];
; #pragma unroll
;           for (int sub = 0; sub < 2; ++sub)
; #pragma unroll
;             for (int m = 0; m < 2; ++m)
; #pragma unroll
;               for (int g = 0; g < 4; ++g) {
;                 float pv[4];
; #pragma unroll
;                 for (int e = 0; e < 4; ++e) pv[e] = exp2_hw(SH ? (Sc[sub][m][4 * g + e] - mbnd[m]) : Sc[sub][m][4 * g + e]);
;                 const unsigned ha = __builtin_bit_cast(unsigned, __builtin_amdgcn_cvt_pkrtz(pv[0], pv[1]));
;                 const unsigned hb = __builtin_bit_cast(unsigned, __builtin_amdgcn_cvt_pkrtz(pv[2], pv[3]));
;                 pf[m][4 * sub + g] = (int)__builtin_amdgcn_perm(hb, ha, 0x07050301u);
;               }
; #pragma unroll
;           for (int mb = 0; mb < 2; ++mb) {
;             const v8i_t vf = *(const v8i_t*)(Vt + (mb * 32 + r) * VL_STRIDE + 32 * hh);
;             O[0][mb] = __builtin_amdgcn_mfma_scale_f32_32x32x64_f8f6f4(vf, pf[0], O[0][mb], 0, 1, 0, 0x7F7F7F7F, 0, 0x7F7F7F7F);
;             O[1][mb] = __builtin_amdgcn_mfma_scale_f32_32x32x64_f8f6f4(vf, pf[1], O[1][mb], 0, 1, 0, 0x7F7F7F7F, 0, 0x7F7F7F7F);
;           }
;           L4[0] = __builtin_amdgcn_mfma_scale_f32_16x16x128_f8f6f4(ones8, pf[0], L4[0], 0, 1, 0, 0x7F7F7F7F, 0, 0x7F7F7F7F);
;           L4[1] = __builtin_amdgcn_mfma_scale_f32_16x16x128_f8f6f4(ones8, pf[1], L4[1], 0, 1, 0, 0x7F7F7F7F, 0, 0x7F7F7F7F);
	s_cbranch_scc1 .Ldiff_lead_s_loop
	s_setprio 3
	s_waitcnt lgkmcnt(0)
	v_mfma_f32_32x32x64_f8f6f4 v[64:79], v[80:87], v[144:151], v[64:79] blgp:1
	v_mfma_f32_32x32x64_f8f6f4 v[96:111], v[80:87], v[160:167], v[96:111] blgp:1
	v_mfma_f32_32x32x64_f8f6f4 v[48:63], v[88:95], v[160:167], v[48:63] blgp:1
	v_mfma_f32_32x32x64_f8f6f4 v[32:47], v[88:95], v[144:151], v[32:47] blgp:1
	v_mfma_f32_16x16x128_f8f6f4 v[196:199], v[2:9], v[160:167], v[196:199] blgp:1
	v_mfma_f32_16x16x128_f8f6f4 v[200:203], v[2:9], v[144:151], v[200:203] blgp:1
	v_mov_b32_e32 v16, -4.0
	v_mov_b32_e32 v17, -4.0
	v_mov_b32_e32 v18, -4.0
	v_mov_b32_e32 v19, -4.0
	v_mov_b32_e32 v20, -4.0
	v_mov_b32_e32 v21, -4.0
	v_mov_b32_e32 v22, -4.0
	v_mov_b32_e32 v23, -4.0
	v_mov_b32_e32 v24, -4.0
	v_mov_b32_e32 v25, -4.0
	v_mov_b32_e32 v26, -4.0
	v_mov_b32_e32 v27, -4.0
	s_nop 7
	s_branch .LBB0_462
.Ldiff_lag_entry:
	v_add_u32_e32 v19, 0x4800, v16
	ds_read_b128 v[204:207], v18
	ds_read_b128 v[80:83], v18 offset:32
	ds_read_b128 v[84:87], v18 offset:64
	ds_read_b128 v[88:91], v18 offset:96
	ds_read_b128 v[92:95], v18 offset:4608
	s_waitcnt lgkmcnt(0)
	v_mfma_f32_32x32x16_bf16 v[160:175], v[204:207], v[10:13], -4.0
	ds_read_b128 v[204:207], v18 offset:4640
	s_waitcnt lgkmcnt(3)
	v_mfma_f32_32x32x16_bf16 v[160:175], v[80:83], v[176:179], v[160:175]
	v_mfma_f32_32x32x16_bf16 v[144:159], v[84:87], v[180:183], -4.0
	ds_read_b128 v[80:83], v18 offset:4672
	ds_read_b128 v[84:87], v18 offset:4704
	s_waitcnt lgkmcnt(3)
	v_mfma_f32_32x32x16_bf16 v[144:159], v[88:91], v[184:187], v[144:159]
	v_mfma_f32_32x32x16_bf16 v[128:143], v[92:95], v[10:13], -4.0
	s_waitcnt lgkmcnt(0)
	v_mfma_f32_32x32x16_bf16 v[128:143], v[204:207], v[176:179], v[128:143]
	v_mfma_f32_32x32x16_bf16 v[112:127], v[80:83], v[180:183], -4.0
	v_mfma_f32_32x32x16_bf16 v[112:127], v[84:87], v[184:187], v[112:127]
	s_cmp_eq_u32 s7, 0
	s_mov_b32 s7, 0x12000
	s_cbranch_scc0 .Ldiff_lag_s_loop
.Ldiff_lag_n_loop:
	s_mul_i32 s18, s17, 0x1800
	s_mov_b32 s19, s13
	v_lshl_add_u64 v[22:23], v[216:217], 0, s[18:19]
	global_load_dwordx4 v[188:191], v[22:23], off offset:512
	s_mul_i32 s18, s16, 0x1800
	s_add_u32 s18, s18, s95
	v_lshl_add_u64 v[24:25], v[216:217], 0, s[18:19]
	global_load_dwordx4 v[192:195], v[24:25], off offset:512
	s_mov_b32 s18, s16
	v_lshl_add_u64 v[26:27], v[218:219], 0, s[18:19]
	global_load_dwordx2 v[222:223], v[26:27], off
	global_load_dwordx2 v[220:221], v[26:27], off offset:64
	ds_read_b128 v[80:83], v20
	ds_read_b128 v[84:87], v20 offset:16
	ds_read_b128 v[88:91], v20 offset:2560
	ds_read_b128 v[92:95], v20 offset:2576
	ds_read_b128 v[204:207], v18 offset:9216
	s_setprio 0
	s_nop 1
	v_exp_f32_e32 v160, v160
	v_exp_f32_e32 v161, v161
	v_exp_f32_e32 v162, v162
	v_exp_f32_e32 v163, v163
	v_exp_f32_e32 v164, v164
	v_exp_f32_e32 v165, v165
	v_exp_f32_e32 v166, v166
	v_exp_f32_e32 v167, v167
	v_cvt_pkrtz_f16_f32 v160, v160, v161
	v_cvt_pkrtz_f16_f32 v161, v162, v163
	v_perm_b32 v160, v161, v160, s1
	v_exp_f32_e32 v168, v168
	v_exp_f32_e32 v169, v169
	v_exp_f32_e32 v170, v170
	v_exp_f32_e32 v171, v171
	v_cvt_pkrtz_f16_f32 v164, v164, v165
	v_cvt_pkrtz_f16_f32 v165, v166, v167
	v_perm_b32 v161, v165, v164, s1
	v_exp_f32_e32 v172, v172
	v_exp_f32_e32 v173, v173
	v_exp_f32_e32 v174, v174
	v_exp_f32_e32 v175, v175
	v_cvt_pkrtz_f16_f32 v168, v168, v169
	v_cvt_pkrtz_f16_f32 v169, v170, v171
	v_perm_b32 v162, v169, v168, s1
	v_exp_f32_e32 v144, v144
	v_exp_f32_e32 v145, v145
	v_exp_f32_e32 v146, v146
	v_exp_f32_e32 v147, v147
	v_cvt_pkrtz_f16_f32 v172, v172, v173
	v_cvt_pkrtz_f16_f32 v173, v174, v175
	v_perm_b32 v163, v173, v172, s1
	v_exp_f32_e32 v148, v148
	v_exp_f32_e32 v149, v149
	v_exp_f32_e32 v150, v150
	v_exp_f32_e32 v151, v151
	v_cvt_pkrtz_f16_f32 v144, v144, v145
	v_cvt_pkrtz_f16_f32 v145, v146, v147
	v_perm_b32 v144, v145, v144, s1
	v_exp_f32_e32 v152, v152
	v_exp_f32_e32 v153, v153
	v_exp_f32_e32 v154, v154
	v_exp_f32_e32 v155, v155
	v_cvt_pkrtz_f16_f32 v148, v148, v149
	v_cvt_pkrtz_f16_f32 v149, v150, v151
	v_perm_b32 v145, v149, v148, s1
	v_exp_f32_e32 v156, v156
	v_exp_f32_e32 v157, v157
	v_exp_f32_e32 v158, v158
	v_exp_f32_e32 v159, v159
	v_cvt_pkrtz_f16_f32 v152, v152, v153
	v_cvt_pkrtz_f16_f32 v153, v154, v155
	v_perm_b32 v146, v153, v152, s1
	v_exp_f32_e32 v128, v128
	v_exp_f32_e32 v129, v129
	v_exp_f32_e32 v130, v130
	v_exp_f32_e32 v131, v131
	v_cvt_pkrtz_f16_f32 v156, v156, v157
	v_cvt_pkrtz_f16_f32 v157, v158, v159
	v_perm_b32 v147, v157, v156, s1
	v_exp_f32_e32 v132, v132
	v_exp_f32_e32 v133, v133
	v_exp_f32_e32 v134, v134
	v_exp_f32_e32 v135, v135
	v_cvt_pkrtz_f16_f32 v128, v128, v129
	v_cvt_pkrtz_f16_f32 v129, v130, v131
	v_perm_b32 v164, v129, v128, s1
	v_exp_f32_e32 v136, v136
	v_exp_f32_e32 v137, v137
	v_exp_f32_e32 v138, v138
	v_exp_f32_e32 v139, v139
	v_cvt_pkrtz_f16_f32 v132, v132, v133
	v_cvt_pkrtz_f16_f32 v133, v134, v135
	v_perm_b32 v165, v133, v132, s1
	v_exp_f32_e32 v140, v140
	v_exp_f32_e32 v141, v141
	v_exp_f32_e32 v142, v142
	v_exp_f32_e32 v143, v143
	v_cvt_pkrtz_f16_f32 v136, v136, v137
	v_cvt_pkrtz_f16_f32 v137, v138, v139
	v_perm_b32 v166, v137, v136, s1
	v_exp_f32_e32 v112, v112
	v_exp_f32_e32 v113, v113
	v_exp_f32_e32 v114, v114
	v_exp_f32_e32 v115, v115
	v_cvt_pkrtz_f16_f32 v140, v140, v141
	v_cvt_pkrtz_f16_f32 v141, v142, v143
	v_perm_b32 v167, v141, v140, s1
	v_exp_f32_e32 v116, v116
	v_exp_f32_e32 v117, v117
	v_exp_f32_e32 v118, v118
	v_exp_f32_e32 v119, v119
	v_cvt_pkrtz_f16_f32 v112, v112, v113
	v_cvt_pkrtz_f16_f32 v113, v114, v115
	v_perm_b32 v148, v113, v112, s1
	v_exp_f32_e32 v120, v120
	v_exp_f32_e32 v121, v121
	v_exp_f32_e32 v122, v122
	v_exp_f32_e32 v123, v123
	v_cvt_pkrtz_f16_f32 v116, v116, v117
	v_cvt_pkrtz_f16_f32 v117, v118, v119
	v_perm_b32 v149, v117, v116, s1
	v_exp_f32_e32 v124, v124
	v_exp_f32_e32 v125, v125
	v_exp_f32_e32 v126, v126
	v_exp_f32_e32 v127, v127
	v_cvt_pkrtz_f16_f32 v120, v120, v121
	v_cvt_pkrtz_f16_f32 v121, v122, v123
	v_perm_b32 v150, v121, v120, s1
	s_nop 0
	v_cvt_pkrtz_f16_f32 v124, v124, v125
	v_cvt_pkrtz_f16_f32 v125, v126, v127
	v_perm_b32 v151, v125, v124, s1
	s_setprio 3
	s_waitcnt lgkmcnt(0)
; #define MFMA32(a, b, c) __builtin_amdgcn_mfma_f32_32x32x16_bf16((a), (b), (c), 0, 0, 0)
; DI float exp2_hw(float x) { return __builtin_amdgcn_exp2f(x); }
; DI void phase_diff(KP p, int layer, u16* sm) {
;     ...
;         for (int hf = 0; hf < 2; ++hf) {
;           const u16* Kt = Ks + buf * (2 * KS_BUF) + hf * KS_BUF;
;           const unsigned char* Vt = Vl + buf * (2 * VL_BUF) + hf * VL_BUF;
;           f32x16 Sc[2][2];
; #pragma unroll
;           for (int sub = 0; sub < 2; ++sub)
; #pragma unroll
;             for (int m = 0; m < 2; ++m) {
; #pragma unroll
;               for (int i = 0; i < 16; ++i) Sc[sub][m][i] = cneg[i];
; #pragma unroll
;               for (int s = 0; s < 2; ++s) {
;                 const bf16x8 kf = *(const bf16x8*)(Kt + (sub * 32 + r) * KS_STRIDE + m * 32 + s * 16 + 8 * hh);
;                 Sc[sub][m] = MFMA32(kf, qf[m][s], Sc[sub][m]);
;               }
;             }
;           v8i_t pf[2];
; #pragma unroll
;           for (int sub = 0; sub < 2; ++sub)
; #pragma unroll
;             for (int m = 0; m < 2; ++m)
; #pragma unroll
;               for (int g = 0; g < 4; ++g) {
;                 float pv[4];
; #pragma unroll
;                 for (int e = 0; e < 4; ++e) pv[e] = exp2_hw(SH ? (Sc[sub][m][4 * g + e] - mbnd[m]) : Sc[sub][m][4 * g + e]);
;                 const unsigned ha = __builtin_bit_cast(unsigned, __builtin_amdgcn_cvt_pkrtz(pv[0], pv[1]));
;                 const unsigned hb = __builtin_bit_cast(unsigned, __builtin_amdgcn_cvt_pkrtz(pv[2], pv[3]));
;                 pf[m][4 * sub + g] = (int)__builtin_amdgcn_perm(hb, ha, 0x07050301u);
;               }
; #pragma unroll
;           for (int mb = 0; mb < 2; ++mb) {
;             const v8i_t vf = *(const v8i_t*)(Vt + (mb * 32 + r) * VL_STRIDE + 32 * hh);
;             O[0][mb] = __builtin_amdgcn_mfma_scale_f32_32x32x64_f8f6f4(vf, pf[0], O[0][mb], 0, 1, 0, 0x7F7F7F7F, 0, 0x7F7F7F7F);
;             O[1][mb] = __builtin_amdgcn_mfma_scale_f32_32x32x64_f8f6f4(vf, pf[1], O[1][mb], 0, 1, 0, 0x7F7F7F7F, 0, 0x7F7F7F7F);
;           }
;           L4[0] = __builtin_amdgcn_mfma_scale_f32_16x16x128_f8f6f4(ones8, pf[0], L4[0], 0, 1, 0, 0x7F7F7F7F, 0, 0x7F7F7F7F);
;           L4[1] = __builtin_amdgcn_mfma_scale_f32_16x16x128_f8f6f4(ones8, pf[1], L4[1], 0, 1, 0, 0x7F7F7F7F, 0, 0x7F7F7F7F);
;         }
;         lstore(buf ^ 1);
;         __syncthreads();
	v_mfma_f32_32x32x64_f8f6f4 v[64:79], v[80:87], v[144:151], v[64:79] blgp:1
	v_mfma_f32_32x32x64_f8f6f4 v[96:111], v[80:87], v[160:167], v[96:111] blgp:1
	ds_read_b128 v[80:83], v18 offset:9248
	ds_read_b128 v[84:87], v18 offset:9280
	v_mfma_f32_32x32x64_f8f6f4 v[48:63], v[88:95], v[160:167], v[48:63] blgp:1
	v_mfma_f32_32x32x64_f8f6f4 v[32:47], v[88:95], v[144:151], v[32:47] blgp:1
	ds_read_b128 v[88:91], v18 offset:9312
	ds_read_b128 v[92:95], v18 offset:13824
	v_mfma_f32_16x16x128_f8f6f4 v[196:199], v[2:9], v[160:167], v[196:199] blgp:1
	v_mfma_f32_16x16x128_f8f6f4 v[200:203], v[2:9], v[144:151], v[200:203] blgp:1
	v_mfma_f32_32x32x16_bf16 v[160:175], v[204:207], v[10:13], -4.0
	ds_read_b128 v[204:207], v18 offset:13856
	s_waitcnt lgkmcnt(3)
	v_mfma_f32_32x32x16_bf16 v[160:175], v[80:83], v[176:179], v[160:175]
	v_mfma_f32_32x32x16_bf16 v[144:159], v[84:87], v[180:183], -4.0
	ds_read_b128 v[80:83], v18 offset:13888
	ds_read_b128 v[84:87], v18 offset:13920
	s_waitcnt lgkmcnt(3)
	v_mfma_f32_32x32x16_bf16 v[144:159], v[88:91], v[184:187], v[144:159]
	v_mfma_f32_32x32x16_bf16 v[128:143], v[92:95], v[10:13], -4.0
	s_waitcnt lgkmcnt(0)
	v_mfma_f32_32x32x16_bf16 v[128:143], v[204:207], v[176:179], v[128:143]
	v_mfma_f32_32x32x16_bf16 v[112:127], v[80:83], v[180:183], -4.0
	v_mfma_f32_32x32x16_bf16 v[112:127], v[84:87], v[184:187], v[112:127]
	ds_read_b128 v[80:83], v20 offset:5120
	ds_read_b128 v[84:87], v20 offset:5136
	ds_read_b128 v[88:91], v20 offset:7680
	ds_read_b128 v[92:95], v20 offset:7696
	ds_read_b128 v[204:207], v19
	s_setprio 0
	s_nop 1
	v_exp_f32_e32 v160, v160
	v_exp_f32_e32 v161, v161
	v_exp_f32_e32 v162, v162
	v_exp_f32_e32 v163, v163
	v_exp_f32_e32 v164, v164
	v_exp_f32_e32 v165, v165
	v_exp_f32_e32 v166, v166
	v_exp_f32_e32 v167, v167
	v_cvt_pkrtz_f16_f32 v160, v160, v161
	v_cvt_pkrtz_f16_f32 v161, v162, v163
	v_perm_b32 v160, v161, v160, s1
	v_exp_f32_e32 v168, v168
	v_exp_f32_e32 v169, v169
	v_exp_f32_e32 v170, v170
	v_exp_f32_e32 v171, v171
	v_cvt_pkrtz_f16_f32 v164, v164, v165
	v_cvt_pkrtz_f16_f32 v165, v166, v167
	v_perm_b32 v161, v165, v164, s1
	v_exp_f32_e32 v172, v172
	v_exp_f32_e32 v173, v173
	v_exp_f32_e32 v174, v174
	v_exp_f32_e32 v175, v175
	v_cvt_pkrtz_f16_f32 v168, v168, v169
	v_cvt_pkrtz_f16_f32 v169, v170, v171
	v_perm_b32 v162, v169, v168, s1
	v_exp_f32_e32 v144, v144
	v_exp_f32_e32 v145, v145
	v_exp_f32_e32 v146, v146
	v_exp_f32_e32 v147, v147
	v_cvt_pkrtz_f16_f32 v172, v172, v173
	v_cvt_pkrtz_f16_f32 v173, v174, v175
	v_perm_b32 v163, v173, v172, s1
	v_exp_f32_e32 v148, v148
	v_exp_f32_e32 v149, v149
	v_exp_f32_e32 v150, v150
	v_exp_f32_e32 v151, v151
	v_cvt_pkrtz_f16_f32 v144, v144, v145
	v_cvt_pkrtz_f16_f32 v145, v146, v147
	v_perm_b32 v144, v145, v144, s1
	v_exp_f32_e32 v152, v152
	v_exp_f32_e32 v153, v153
	v_exp_f32_e32 v154, v154
	v_exp_f32_e32 v155, v155
	v_cvt_pkrtz_f16_f32 v148, v148, v149
	v_cvt_pkrtz_f16_f32 v149, v150, v151
	v_perm_b32 v145, v149, v148, s1
	v_exp_f32_e32 v156, v156
	v_exp_f32_e32 v157, v157
	v_exp_f32_e32 v158, v158
	v_exp_f32_e32 v159, v159
	v_cvt_pkrtz_f16_f32 v152, v152, v153
	v_cvt_pkrtz_f16_f32 v153, v154, v155
	v_perm_b32 v146, v153, v152, s1
	v_exp_f32_e32 v128, v128
	v_exp_f32_e32 v129, v129
	v_exp_f32_e32 v130, v130
	v_exp_f32_e32 v131, v131
	v_cvt_pkrtz_f16_f32 v156, v156, v157
	v_cvt_pkrtz_f16_f32 v157, v158, v159
	v_perm_b32 v147, v157, v156, s1
	v_exp_f32_e32 v132, v132
	v_exp_f32_e32 v133, v133
	v_exp_f32_e32 v134, v134
	v_exp_f32_e32 v135, v135
	v_cvt_pkrtz_f16_f32 v128, v128, v129
	v_cvt_pkrtz_f16_f32 v129, v130, v131
	v_perm_b32 v164, v129, v128, s1
	v_exp_f32_e32 v136, v136
	v_exp_f32_e32 v137, v137
	v_exp_f32_e32 v138, v138
	v_exp_f32_e32 v139, v139
	v_cvt_pkrtz_f16_f32 v132, v132, v133
	v_cvt_pkrtz_f16_f32 v133, v134, v135
	v_perm_b32 v165, v133, v132, s1
	v_exp_f32_e32 v140, v140
	v_exp_f32_e32 v141, v141
	v_exp_f32_e32 v142, v142
	v_exp_f32_e32 v143, v143
	v_cvt_pkrtz_f16_f32 v136, v136, v137
	v_cvt_pkrtz_f16_f32 v137, v138, v139
	v_perm_b32 v166, v137, v136, s1
	v_exp_f32_e32 v112, v112
	v_exp_f32_e32 v113, v113
	v_exp_f32_e32 v114, v114
	v_exp_f32_e32 v115, v115
	v_cvt_pkrtz_f16_f32 v140, v140, v141
	v_cvt_pkrtz_f16_f32 v141, v142, v143
	v_perm_b32 v167, v141, v140, s1
	v_exp_f32_e32 v116, v116
	v_exp_f32_e32 v117, v117
	v_exp_f32_e32 v118, v118
	v_exp_f32_e32 v119, v119
	v_cvt_pkrtz_f16_f32 v112, v112, v113
	v_cvt_pkrtz_f16_f32 v113, v114, v115
	v_perm_b32 v148, v113, v112, s1
	v_exp_f32_e32 v120, v120
	v_exp_f32_e32 v121, v121
	v_exp_f32_e32 v122, v122
	v_exp_f32_e32 v123, v123
	v_cvt_pkrtz_f16_f32 v116, v116, v117
	v_cvt_pkrtz_f16_f32 v117, v118, v119
	v_perm_b32 v149, v117, v116, s1
	v_exp_f32_e32 v124, v124
	v_exp_f32_e32 v125, v125
	v_exp_f32_e32 v126, v126
	v_exp_f32_e32 v127, v127
	v_cvt_pkrtz_f16_f32 v120, v120, v121
	v_cvt_pkrtz_f16_f32 v121, v122, v123
	v_perm_b32 v150, v121, v120, s1
	s_nop 0
	v_cvt_pkrtz_f16_f32 v124, v124, v125
	v_cvt_pkrtz_f16_f32 v125, v126, v127
	v_perm_b32 v151, v125, v124, s1
	s_waitcnt vmcnt(0)
	v_add_u32_e32 v112, s99, v250
	ds_write_b128 v112, v[188:191]
	v_add_u32_e32 v113, s100, v250
	ds_write_b128 v113, v[192:195] offset:9216
	v_add_u32_e32 v114, s101, v251
	ds_write2_b32 v114, v222, v223 offset1:8
	v_add_u32_e32 v115, 0x1400, v114
	ds_write2_b32 v115, v220, v221 offset1:8
	s_setprio 3
	s_waitcnt lgkmcnt(4)
; DI void phase_diff(KP p, int layer, u16* sm) {
;     ...
;     auto lstore = [&](int buf) __attribute__((always_inline)) {
;       u16* kd = Ks + buf * (2 * KS_BUF) + key0 * KS_STRIDE + ch * 8;
;       *(uint4*)kd = kra; *(uint4*)(kd + KS_BUF) = krb;
;       unsigned char* vd = Vl + buf * (2 * VL_BUF) + key0 * VL_STRIDE + 4 * ch;
;       *(unsigned*)vd = vra.x; *(unsigned*)(vd + 32) = vra.y;
;       *(unsigned*)(vd + VL_BUF) = vrb.x; *(unsigned*)(vd + VL_BUF + 32) = vrb.y;
;     };
;     gload(0); lstore(0);
;     __syncthreads();
;     if (w >= 4) __builtin_amdgcn_s_setprio(1);
;     auto tile_loop = [&](auto shifted) __attribute__((always_inline)) {
;       constexpr bool SH = decltype(shifted)::value;
;       for (int st = 0; st < 128; ++st) {
;         const int buf = st & 1;
;         gload(st + 1);
; #pragma unroll
;         for (int hf = 0; hf < 2; ++hf) {
;           const u16* Kt = Ks + buf * (2 * KS_BUF) + hf * KS_BUF;
;           const unsigned char* Vt = Vl + buf * (2 * VL_BUF) + hf * VL_BUF;
;           f32x16 Sc[2][2];
; #pragma unroll
;           for (int sub = 0; sub < 2; ++sub)
; #pragma unroll
;             for (int m = 0; m < 2; ++m) {
; #pragma unroll
;               for (int i = 0; i < 16; ++i) Sc[sub][m][i] = cneg[i];
; #pragma unroll
;               for (int s = 0; s < 2; ++s) {
;                 const bf16x8 kf = *(const bf16x8*)(Kt + (sub * 32 + r) * KS_STRIDE + m * 32 + s * 16 + 8 * hh);
;                 Sc[sub][m] = MFMA32(kf, qf[m][s], Sc[sub][m]);
;               }
;             }
;           v8i_t pf[2];
; #pragma unroll
;           for (int sub = 0; sub < 2; ++sub)
; #pragma unroll
;             for (int m = 0; m < 2; ++m)
; #pragma unroll
;               for (int g = 0; g < 4; ++g) {
;                 float pv[4];
; #pragma unroll
;                 for (int e = 0; e < 4; ++e) pv[e] = exp2_hw(SH ? (Sc[sub][m][4 * g + e] - mbnd[m]) : Sc[sub][m][4 * g + e]);
;                 const unsigned ha = __builtin_bit_cast(unsigned, __builtin_amdgcn_cvt_pkrtz(pv[0], pv[1]));
;                 const unsigned hb = __builtin_bit_cast(unsigned, __builtin_amdgcn_cvt_pkrtz(pv[2], pv[3]));
;                 pf[m][4 * sub + g] = (int)__builtin_amdgcn_perm(hb, ha, 0x07050301u);
;               }
; #pragma unroll
;           for (int mb = 0; mb < 2; ++mb) {
;             const v8i_t vf = *(const v8i_t*)(Vt + (mb * 32 + r) * VL_STRIDE + 32 * hh);
	v_mfma_f32_32x32x64_f8f6f4 v[64:79], v[80:87], v[144:151], v[64:79] blgp:1
	v_mfma_f32_32x32x64_f8f6f4 v[96:111], v[80:87], v[160:167], v[96:111] blgp:1
	ds_read_b128 v[80:83], v19 offset:32
	ds_read_b128 v[84:87], v19 offset:64
	v_mfma_f32_32x32x64_f8f6f4 v[48:63], v[88:95], v[160:167], v[48:63] blgp:1
	v_mfma_f32_32x32x64_f8f6f4 v[32:47], v[88:95], v[144:151], v[32:47] blgp:1
	ds_read_b128 v[88:91], v19 offset:96
	ds_read_b128 v[92:95], v19 offset:4608
	v_mfma_f32_16x16x128_f8f6f4 v[196:199], v[2:9], v[160:167], v[196:199] blgp:1
	v_mfma_f32_16x16x128_f8f6f4 v[200:203], v[2:9], v[144:151], v[200:203] blgp:1
	v_mfma_f32_32x32x16_bf16 v[160:175], v[204:207], v[10:13], -4.0
	ds_read_b128 v[204:207], v19 offset:4640
	s_waitcnt lgkmcnt(3)
	v_mfma_f32_32x32x16_bf16 v[160:175], v[80:83], v[176:179], v[160:175]
	v_mfma_f32_32x32x16_bf16 v[144:159], v[84:87], v[180:183], -4.0
	ds_read_b128 v[80:83], v19 offset:4672
	ds_read_b128 v[84:87], v19 offset:4704
	s_waitcnt lgkmcnt(3)
	v_mfma_f32_32x32x16_bf16 v[144:159], v[88:91], v[184:187], v[144:159]
	v_mfma_f32_32x32x16_bf16 v[128:143], v[92:95], v[10:13], -4.0
	s_waitcnt lgkmcnt(0)
	v_mfma_f32_32x32x16_bf16 v[128:143], v[204:207], v[176:179], v[128:143]
	v_mfma_f32_32x32x16_bf16 v[112:127], v[80:83], v[180:183], -4.0
	v_mfma_f32_32x32x16_bf16 v[112:127], v[84:87], v[184:187], v[112:127]
	s_mov_b32 s98, s100
	s_mov_b32 s100, s99
	s_add_i32 s99, s99, 0x4800
	s_cmp_eq_u32 s99, 0x12000
	s_cselect_b32 s99, 0, s99
	s_mov_b32 s7, s101
	s_add_i32 s101, s101, 0x2800
	s_cmp_eq_u32 s101, 0x1c000
	s_cselect_b32 s101, 0x12000, s101
	s_mov_b32 s16, s17
	s_add_i32 s17, s17, 0x80
	s_and_b32 s17, s17, 0x3fff
	v_add_u32_e32 v18, s98, v16
	v_add_u32_e32 v20, s7, v17
	v_add_u32_e32 v19, s100, v16
	s_add_i32 s6, s6, 1
	s_cmpk_lt_u32 s6, 0x80
	s_waitcnt lgkmcnt(0)
	s_barrier
	s_cbranch_scc1 .Ldiff_lag_n_loop
	v_mov_b32_e32 v16, -4.0
	v_mov_b32_e32 v17, -4.0
	v_mov_b32_e32 v18, -4.0
	v_mov_b32_e32 v19, -4.0
	v_mov_b32_e32 v20, -4.0
	v_mov_b32_e32 v21, -4.0
	v_mov_b32_e32 v22, -4.0
	v_mov_b32_e32 v23, -4.0
	v_mov_b32_e32 v24, -4.0
	v_mov_b32_e32 v25, -4.0
	v_mov_b32_e32 v26, -4.0
	v_mov_b32_e32 v27, -4.0
	s_nop 7
	s_branch .LBB0_462
.Ldiff_lag_s_loop:
	s_mul_i32 s18, s17, 0x1800
	s_mov_b32 s19, s13
	v_lshl_add_u64 v[22:23], v[216:217], 0, s[18:19]
	global_load_dwordx4 v[188:191], v[22:23], off offset:512
	s_mul_i32 s18, s16, 0x1800
	s_add_u32 s18, s18, s95
	v_lshl_add_u64 v[24:25], v[216:217], 0, s[18:19]
	global_load_dwordx4 v[192:195], v[24:25], off offset:512
	s_mov_b32 s18, s16
	v_lshl_add_u64 v[26:27], v[218:219], 0, s[18:19]
	global_load_dwordx2 v[222:223], v[26:27], off
	global_load_dwordx2 v[220:221], v[26:27], off offset:64
	ds_read_b128 v[80:83], v20
	ds_read_b128 v[84:87], v20 offset:16
	ds_read_b128 v[88:91], v20 offset:2560
	ds_read_b128 v[92:95], v20 offset:2576
	ds_read_b128 v[204:207], v18 offset:9216
	s_setprio 0
	s_nop 1
	v_sub_f32_e32 v160, v160, v213
	v_sub_f32_e32 v161, v161, v213
	v_sub_f32_e32 v162, v162, v213
	v_sub_f32_e32 v163, v163, v213
	v_exp_f32_e32 v160, v160
	v_exp_f32_e32 v161, v161
	v_exp_f32_e32 v162, v162
	v_exp_f32_e32 v163, v163
	v_sub_f32_e32 v164, v164, v213
	v_sub_f32_e32 v165, v165, v213
	v_sub_f32_e32 v166, v166, v213
	v_sub_f32_e32 v167, v167, v213
	v_exp_f32_e32 v164, v164
	v_exp_f32_e32 v165, v165
	v_exp_f32_e32 v166, v166
	v_exp_f32_e32 v167, v167
	v_cvt_pkrtz_f16_f32 v160, v160, v161
	v_cvt_pkrtz_f16_f32 v161, v162, v163
	v_perm_b32 v160, v161, v160, s1
	v_sub_f32_e32 v168, v168, v213
	v_sub_f32_e32 v169, v169, v213
	v_sub_f32_e32 v170, v170, v213
	v_sub_f32_e32 v171, v171, v213
	v_exp_f32_e32 v168, v168
	v_exp_f32_e32 v169, v169
	v_exp_f32_e32 v170, v170
	v_exp_f32_e32 v171, v171
	v_cvt_pkrtz_f16_f32 v164, v164, v165
	v_cvt_pkrtz_f16_f32 v165, v166, v167
	v_perm_b32 v161, v165, v164, s1
	v_sub_f32_e32 v172, v172, v213
	v_sub_f32_e32 v173, v173, v213
	v_sub_f32_e32 v174, v174, v213
	v_sub_f32_e32 v175, v175, v213
	v_exp_f32_e32 v172, v172
	v_exp_f32_e32 v173, v173
	v_exp_f32_e32 v174, v174
	v_exp_f32_e32 v175, v175
	v_cvt_pkrtz_f16_f32 v168, v168, v169
	v_cvt_pkrtz_f16_f32 v169, v170, v171
	v_perm_b32 v162, v169, v168, s1
	v_sub_f32_e32 v144, v144, v237
	v_sub_f32_e32 v145, v145, v237
	v_sub_f32_e32 v146, v146, v237
	v_sub_f32_e32 v147, v147, v237
	v_exp_f32_e32 v144, v144
	v_exp_f32_e32 v145, v145
	v_exp_f32_e32 v146, v146
	v_exp_f32_e32 v147, v147
	v_cvt_pkrtz_f16_f32 v172, v172, v173
	v_cvt_pkrtz_f16_f32 v173, v174, v175
	v_perm_b32 v163, v173, v172, s1
	v_sub_f32_e32 v148, v148, v237
	v_sub_f32_e32 v149, v149, v237
	v_sub_f32_e32 v150, v150, v237
	v_sub_f32_e32 v151, v151, v237
	v_exp_f32_e32 v148, v148
	v_exp_f32_e32 v149, v149
	v_exp_f32_e32 v150, v150
	v_exp_f32_e32 v151, v151
	v_cvt_pkrtz_f16_f32 v144, v144, v145
	v_cvt_pkrtz_f16_f32 v145, v146, v147
	v_perm_b32 v144, v145, v144, s1
	v_sub_f32_e32 v152, v152, v237
	v_sub_f32_e32 v153, v153, v237
	v_sub_f32_e32 v154, v154, v237
	v_sub_f32_e32 v155, v155, v237
	v_exp_f32_e32 v152, v152
	v_exp_f32_e32 v153, v153
	v_exp_f32_e32 v154, v154
	v_exp_f32_e32 v155, v155
	v_cvt_pkrtz_f16_f32 v148, v148, v149
	v_cvt_pkrtz_f16_f32 v149, v150, v151
	v_perm_b32 v145, v149, v148, s1
	v_sub_f32_e32 v156, v156, v237
	v_sub_f32_e32 v157, v157, v237
	v_sub_f32_e32 v158, v158, v237
	v_sub_f32_e32 v159, v159, v237
	v_exp_f32_e32 v156, v156
	v_exp_f32_e32 v157, v157
	v_exp_f32_e32 v158, v158
	v_exp_f32_e32 v159, v159
	v_cvt_pkrtz_f16_f32 v152, v152, v153
	v_cvt_pkrtz_f16_f32 v153, v154, v155
	v_perm_b32 v146, v153, v152, s1
	v_sub_f32_e32 v128, v128, v213
	v_sub_f32_e32 v129, v129, v213
	v_sub_f32_e32 v130, v130, v213
; #define MFMA32(a, b, c) __builtin_amdgcn_mfma_f32_32x32x16_bf16((a), (b), (c), 0, 0, 0)
; DI float exp2_hw(float x) { return __builtin_amdgcn_exp2f(x); }
; DI void phase_diff(KP p, int layer, u16* sm) {
;     ...
;         for (int hf = 0; hf < 2; ++hf) {
;           const u16* Kt = Ks + buf * (2 * KS_BUF) + hf * KS_BUF;
;           const unsigned char* Vt = Vl + buf * (2 * VL_BUF) + hf * VL_BUF;
;           f32x16 Sc[2][2];
; #pragma unroll
;           for (int sub = 0; sub < 2; ++sub)
; #pragma unroll
;             for (int m = 0; m < 2; ++m) {
; #pragma unroll
;               for (int i = 0; i < 16; ++i) Sc[sub][m][i] = cneg[i];
; #pragma unroll
;               for (int s = 0; s < 2; ++s) {
;                 const bf16x8 kf = *(const bf16x8*)(Kt + (sub * 32 + r) * KS_STRIDE + m * 32 + s * 16 + 8 * hh);
;                 Sc[sub][m] = MFMA32(kf, qf[m][s], Sc[sub][m]);
;               }
;             }
;           v8i_t pf[2];
; #pragma unroll
;           for (int sub = 0; sub < 2; ++sub)
; #pragma unroll
;             for (int m = 0; m < 2; ++m)
; #pragma unroll
;               for (int g = 0; g < 4; ++g) {
;                 float pv[4];
; #pragma unroll
;                 for (int e = 0; e < 4; ++e) pv[e] = exp2_hw(SH ? (Sc[sub][m][4 * g + e] - mbnd[m]) : Sc[sub][m][4 * g + e]);
;                 const unsigned ha = __builtin_bit_cast(unsigned, __builtin_amdgcn_cvt_pkrtz(pv[0], pv[1]));
;                 const unsigned hb = __builtin_bit_cast(unsigned, __builtin_amdgcn_cvt_pkrtz(pv[2], pv[3]));
;                 pf[m][4 * sub + g] = (int)__builtin_amdgcn_perm(hb, ha, 0x07050301u);
;               }
; #pragma unroll
;           for (int mb = 0; mb < 2; ++mb) {
;             const v8i_t vf = *(const v8i_t*)(Vt + (mb * 32 + r) * VL_STRIDE + 32 * hh);
;             O[0][mb] = __builtin_amdgcn_mfma_scale_f32_32x32x64_f8f6f4(vf, pf[0], O[0][mb], 0, 1, 0, 0x7F7F7F7F, 0, 0x7F7F7F7F);
;             O[1][mb] = __builtin_amdgcn_mfma_scale_f32_32x32x64_f8f6f4(vf, pf[1], O[1][mb], 0, 1, 0, 0x7F7F7F7F, 0, 0x7F7F7F7F);
;           }
;           L4[0] = __builtin_amdgcn_mfma_scale_f32_16x16x128_f8f6f4(ones8, pf[0], L4[0], 0, 1, 0, 0x7F7F7F7F, 0, 0x7F7F7F7F);
;           L4[1] = __builtin_amdgcn_mfma_scale_f32_16x16x128_f8f6f4(ones8, pf[1], L4[1], 0, 1, 0, 0x7F7F7F7F, 0, 0x7F7F7F7F);
	v_sub_f32_e32 v131, v131, v213
	v_exp_f32_e32 v128, v128
	v_exp_f32_e32 v129, v129
	v_exp_f32_e32 v130, v130
	v_exp_f32_e32 v131, v131
	v_cvt_pkrtz_f16_f32 v156, v156, v157
	v_cvt_pkrtz_f16_f32 v157, v158, v159
	v_perm_b32 v147, v157, v156, s1
	v_sub_f32_e32 v132, v132, v213
	v_sub_f32_e32 v133, v133, v213
	v_sub_f32_e32 v134, v134, v213
	v_sub_f32_e32 v135, v135, v213
	v_exp_f32_e32 v132, v132
	v_exp_f32_e32 v133, v133
	v_exp_f32_e32 v134, v134
	v_exp_f32_e32 v135, v135
	v_cvt_pkrtz_f16_f32 v128, v128, v129
	v_cvt_pkrtz_f16_f32 v129, v130, v131
	v_perm_b32 v164, v129, v128, s1
	v_sub_f32_e32 v136, v136, v213
	v_sub_f32_e32 v137, v137, v213
	v_sub_f32_e32 v138, v138, v213
	v_sub_f32_e32 v139, v139, v213
	v_exp_f32_e32 v136, v136
	v_exp_f32_e32 v137, v137
	v_exp_f32_e32 v138, v138
	v_exp_f32_e32 v139, v139
	v_cvt_pkrtz_f16_f32 v132, v132, v133
	v_cvt_pkrtz_f16_f32 v133, v134, v135
	v_perm_b32 v165, v133, v132, s1
	v_sub_f32_e32 v140, v140, v213
	v_sub_f32_e32 v141, v141, v213
	v_sub_f32_e32 v142, v142, v213
	v_sub_f32_e32 v143, v143, v213
	v_exp_f32_e32 v140, v140
	v_exp_f32_e32 v141, v141
	v_exp_f32_e32 v142, v142
	v_exp_f32_e32 v143, v143
	v_cvt_pkrtz_f16_f32 v136, v136, v137
	v_cvt_pkrtz_f16_f32 v137, v138, v139
	v_perm_b32 v166, v137, v136, s1
	v_sub_f32_e32 v112, v112, v237
	v_sub_f32_e32 v113, v113, v237
	v_sub_f32_e32 v114, v114, v237
	v_sub_f32_e32 v115, v115, v237
	v_exp_f32_e32 v112, v112
	v_exp_f32_e32 v113, v113
	v_exp_f32_e32 v114, v114
	v_exp_f32_e32 v115, v115
	v_cvt_pkrtz_f16_f32 v140, v140, v141
	v_cvt_pkrtz_f16_f32 v141, v142, v143
	v_perm_b32 v167, v141, v140, s1
	v_sub_f32_e32 v116, v116, v237
	v_sub_f32_e32 v117, v117, v237
	v_sub_f32_e32 v118, v118, v237
	v_sub_f32_e32 v119, v119, v237
	v_exp_f32_e32 v116, v116
	v_exp_f32_e32 v117, v117
	v_exp_f32_e32 v118, v118
	v_exp_f32_e32 v119, v119
	v_cvt_pkrtz_f16_f32 v112, v112, v113
	v_cvt_pkrtz_f16_f32 v113, v114, v115
	v_perm_b32 v148, v113, v112, s1
	v_sub_f32_e32 v120, v120, v237
	v_sub_f32_e32 v121, v121, v237
	v_sub_f32_e32 v122, v122, v237
	v_sub_f32_e32 v123, v123, v237
	v_exp_f32_e32 v120, v120
	v_exp_f32_e32 v121, v121
	v_exp_f32_e32 v122, v122
	v_exp_f32_e32 v123, v123
	v_cvt_pkrtz_f16_f32 v116, v116, v117
	v_cvt_pkrtz_f16_f32 v117, v118, v119
	v_perm_b32 v149, v117, v116, s1
	v_sub_f32_e32 v124, v124, v237
	v_sub_f32_e32 v125, v125, v237
	v_sub_f32_e32 v126, v126, v237
	v_sub_f32_e32 v127, v127, v237
	v_exp_f32_e32 v124, v124
	v_exp_f32_e32 v125, v125
	v_exp_f32_e32 v126, v126
	v_exp_f32_e32 v127, v127
	v_cvt_pkrtz_f16_f32 v120, v120, v121
	v_cvt_pkrtz_f16_f32 v121, v122, v123
	v_perm_b32 v150, v121, v120, s1
	s_nop 0
	v_cvt_pkrtz_f16_f32 v124, v124, v125
	v_cvt_pkrtz_f16_f32 v125, v126, v127
	v_perm_b32 v151, v125, v124, s1
	s_setprio 3
	s_waitcnt lgkmcnt(0)
	v_mfma_f32_32x32x64_f8f6f4 v[64:79], v[80:87], v[144:151], v[64:79] blgp:1
	v_mfma_f32_32x32x64_f8f6f4 v[96:111], v[80:87], v[160:167], v[96:111] blgp:1
	ds_read_b128 v[80:83], v18 offset:9248
	ds_read_b128 v[84:87], v18 offset:9280
	v_mfma_f32_32x32x64_f8f6f4 v[48:63], v[88:95], v[160:167], v[48:63] blgp:1
	v_mfma_f32_32x32x64_f8f6f4 v[32:47], v[88:95], v[144:151], v[32:47] blgp:1
	ds_read_b128 v[88:91], v18 offset:9312
	ds_read_b128 v[92:95], v18 offset:13824
	v_mfma_f32_16x16x128_f8f6f4 v[196:199], v[2:9], v[160:167], v[196:199] blgp:1
	v_mfma_f32_16x16x128_f8f6f4 v[200:203], v[2:9], v[144:151], v[200:203] blgp:1
	v_mfma_f32_32x32x16_bf16 v[160:175], v[204:207], v[10:13], -4.0
	ds_read_b128 v[204:207], v18 offset:13856
	s_waitcnt lgkmcnt(3)
	v_mfma_f32_32x32x16_bf16 v[160:175], v[80:83], v[176:179], v[160:175]
	v_mfma_f32_32x32x16_bf16 v[144:159], v[84:87], v[180:183], -4.0
	ds_read_b128 v[80:83], v18 offset:13888
	ds_read_b128 v[84:87], v18 offset:13920
	s_waitcnt lgkmcnt(3)
	v_mfma_f32_32x32x16_bf16 v[144:159], v[88:91], v[184:187], v[144:159]
	v_mfma_f32_32x32x16_bf16 v[128:143], v[92:95], v[10:13], -4.0
	s_waitcnt lgkmcnt(0)
	v_mfma_f32_32x32x16_bf16 v[128:143], v[204:207], v[176:179], v[128:143]
	v_mfma_f32_32x32x16_bf16 v[112:127], v[80:83], v[180:183], -4.0
	v_mfma_f32_32x32x16_bf16 v[112:127], v[84:87], v[184:187], v[112:127]
	ds_read_b128 v[80:83], v20 offset:5120
	ds_read_b128 v[84:87], v20 offset:5136
	ds_read_b128 v[88:91], v20 offset:7680
	ds_read_b128 v[92:95], v20 offset:7696
	ds_read_b128 v[204:207], v19
	s_setprio 0
	s_nop 1
	v_sub_f32_e32 v160, v160, v213
	v_sub_f32_e32 v161, v161, v213
	v_sub_f32_e32 v162, v162, v213
	v_sub_f32_e32 v163, v163, v213
	v_exp_f32_e32 v160, v160
	v_exp_f32_e32 v161, v161
	v_exp_f32_e32 v162, v162
	v_exp_f32_e32 v163, v163
	v_sub_f32_e32 v164, v164, v213
	v_sub_f32_e32 v165, v165, v213
	v_sub_f32_e32 v166, v166, v213
	v_sub_f32_e32 v167, v167, v213
	v_exp_f32_e32 v164, v164
	v_exp_f32_e32 v165, v165
	v_exp_f32_e32 v166, v166
	v_exp_f32_e32 v167, v167
	v_cvt_pkrtz_f16_f32 v160, v160, v161
	v_cvt_pkrtz_f16_f32 v161, v162, v163
	v_perm_b32 v160, v161, v160, s1
	v_sub_f32_e32 v168, v168, v213
	v_sub_f32_e32 v169, v169, v213
	v_sub_f32_e32 v170, v170, v213
	v_sub_f32_e32 v171, v171, v213
	v_exp_f32_e32 v168, v168
	v_exp_f32_e32 v169, v169
	v_exp_f32_e32 v170, v170
	v_exp_f32_e32 v171, v171
	v_cvt_pkrtz_f16_f32 v164, v164, v165
	v_cvt_pkrtz_f16_f32 v165, v166, v167
	v_perm_b32 v161, v165, v164, s1
	v_sub_f32_e32 v172, v172, v213
	v_sub_f32_e32 v173, v173, v213
	v_sub_f32_e32 v174, v174, v213
	v_sub_f32_e32 v175, v175, v213
	v_exp_f32_e32 v172, v172
	v_exp_f32_e32 v173, v173
	v_exp_f32_e32 v174, v174
	v_exp_f32_e32 v175, v175
	v_cvt_pkrtz_f16_f32 v168, v168, v169
	v_cvt_pkrtz_f16_f32 v169, v170, v171
	v_perm_b32 v162, v169, v168, s1
	v_sub_f32_e32 v144, v144, v237
; DI void phase_diff(KP p, int layer, u16* sm) {
;     ...
;     auto lstore = [&](int buf) __attribute__((always_inline)) {
;       u16* kd = Ks + buf * (2 * KS_BUF) + key0 * KS_STRIDE + ch * 8;
;       *(uint4*)kd = kra; *(uint4*)(kd + KS_BUF) = krb;
;       unsigned char* vd = Vl + buf * (2 * VL_BUF) + key0 * VL_STRIDE + 4 * ch;
;       *(unsigned*)vd = vra.x; *(unsigned*)(vd + 32) = vra.y;
;       *(unsigned*)(vd + VL_BUF) = vrb.x; *(unsigned*)(vd + VL_BUF + 32) = vrb.y;
;     };
;     gload(0); lstore(0);
;     __syncthreads();
;     if (w >= 4) __builtin_amdgcn_s_setprio(1);
;     auto tile_loop = [&](auto shifted) __attribute__((always_inline)) {
;       constexpr bool SH = decltype(shifted)::value;
;       for (int st = 0; st < 128; ++st) {
;         const int buf = st & 1;
;         gload(st + 1);
; #pragma unroll
;         for (int hf = 0; hf < 2; ++hf) {
;           const u16* Kt = Ks + buf * (2 * KS_BUF) + hf * KS_BUF;
;           const unsigned char* Vt = Vl + buf * (2 * VL_BUF) + hf * VL_BUF;
;           f32x16 Sc[2][2];
; #pragma unroll
;           for (int sub = 0; sub < 2; ++sub)
; #pragma unroll
;             for (int m = 0; m < 2; ++m) {
; #pragma unroll
;               for (int i = 0; i < 16; ++i) Sc[sub][m][i] = cneg[i];
; #pragma unroll
;               for (int s = 0; s < 2; ++s) {
;                 const bf16x8 kf = *(const bf16x8*)(Kt + (sub * 32 + r) * KS_STRIDE + m * 32 + s * 16 + 8 * hh);
;                 Sc[sub][m] = MFMA32(kf, qf[m][s], Sc[sub][m]);
;               }
;             }
;           v8i_t pf[2];
; #pragma unroll
;           for (int sub = 0; sub < 2; ++sub)
; #pragma unroll
;             for (int m = 0; m < 2; ++m)
; #pragma unroll
;               for (int g = 0; g < 4; ++g) {
;                 float pv[4];
; #pragma unroll
;                 for (int e = 0; e < 4; ++e) pv[e] = exp2_hw(SH ? (Sc[sub][m][4 * g + e] - mbnd[m]) : Sc[sub][m][4 * g + e]);
;                 const unsigned ha = __builtin_bit_cast(unsigned, __builtin_amdgcn_cvt_pkrtz(pv[0], pv[1]));
;                 const unsigned hb = __builtin_bit_cast(unsigned, __builtin_amdgcn_cvt_pkrtz(pv[2], pv[3]));
;                 pf[m][4 * sub + g] = (int)__builtin_amdgcn_perm(hb, ha, 0x07050301u);
;               }
; #pragma unroll
;           for (int mb = 0; mb < 2; ++mb) {
;             const v8i_t vf = *(const v8i_t*)(Vt + (mb * 32 + r) * VL_STRIDE + 32 * hh);
	v_sub_f32_e32 v145, v145, v237
	v_sub_f32_e32 v146, v146, v237
	v_sub_f32_e32 v147, v147, v237
	v_exp_f32_e32 v144, v144
	v_exp_f32_e32 v145, v145
	v_exp_f32_e32 v146, v146
	v_exp_f32_e32 v147, v147
	v_cvt_pkrtz_f16_f32 v172, v172, v173
	v_cvt_pkrtz_f16_f32 v173, v174, v175
	v_perm_b32 v163, v173, v172, s1
	v_sub_f32_e32 v148, v148, v237
	v_sub_f32_e32 v149, v149, v237
	v_sub_f32_e32 v150, v150, v237
	v_sub_f32_e32 v151, v151, v237
	v_exp_f32_e32 v148, v148
	v_exp_f32_e32 v149, v149
	v_exp_f32_e32 v150, v150
	v_exp_f32_e32 v151, v151
	v_cvt_pkrtz_f16_f32 v144, v144, v145
	v_cvt_pkrtz_f16_f32 v145, v146, v147
	v_perm_b32 v144, v145, v144, s1
	v_sub_f32_e32 v152, v152, v237
	v_sub_f32_e32 v153, v153, v237
	v_sub_f32_e32 v154, v154, v237
	v_sub_f32_e32 v155, v155, v237
	v_exp_f32_e32 v152, v152
	v_exp_f32_e32 v153, v153
	v_exp_f32_e32 v154, v154
	v_exp_f32_e32 v155, v155
	v_cvt_pkrtz_f16_f32 v148, v148, v149
	v_cvt_pkrtz_f16_f32 v149, v150, v151
	v_perm_b32 v145, v149, v148, s1
	v_sub_f32_e32 v156, v156, v237
	v_sub_f32_e32 v157, v157, v237
	v_sub_f32_e32 v158, v158, v237
	v_sub_f32_e32 v159, v159, v237
	v_exp_f32_e32 v156, v156
	v_exp_f32_e32 v157, v157
	v_exp_f32_e32 v158, v158
	v_exp_f32_e32 v159, v159
	v_cvt_pkrtz_f16_f32 v152, v152, v153
	v_cvt_pkrtz_f16_f32 v153, v154, v155
	v_perm_b32 v146, v153, v152, s1
	v_sub_f32_e32 v128, v128, v213
	v_sub_f32_e32 v129, v129, v213
	v_sub_f32_e32 v130, v130, v213
	v_sub_f32_e32 v131, v131, v213
	v_exp_f32_e32 v128, v128
	v_exp_f32_e32 v129, v129
	v_exp_f32_e32 v130, v130
	v_exp_f32_e32 v131, v131
	v_cvt_pkrtz_f16_f32 v156, v156, v157
	v_cvt_pkrtz_f16_f32 v157, v158, v159
	v_perm_b32 v147, v157, v156, s1
	v_sub_f32_e32 v132, v132, v213
	v_sub_f32_e32 v133, v133, v213
	v_sub_f32_e32 v134, v134, v213
	v_sub_f32_e32 v135, v135, v213
	v_exp_f32_e32 v132, v132
	v_exp_f32_e32 v133, v133
	v_exp_f32_e32 v134, v134
	v_exp_f32_e32 v135, v135
	v_cvt_pkrtz_f16_f32 v128, v128, v129
	v_cvt_pkrtz_f16_f32 v129, v130, v131
	v_perm_b32 v164, v129, v128, s1
	v_sub_f32_e32 v136, v136, v213
	v_sub_f32_e32 v137, v137, v213
	v_sub_f32_e32 v138, v138, v213
	v_sub_f32_e32 v139, v139, v213
	v_exp_f32_e32 v136, v136
	v_exp_f32_e32 v137, v137
	v_exp_f32_e32 v138, v138
	v_exp_f32_e32 v139, v139
	v_cvt_pkrtz_f16_f32 v132, v132, v133
	v_cvt_pkrtz_f16_f32 v133, v134, v135
	v_perm_b32 v165, v133, v132, s1
	v_sub_f32_e32 v140, v140, v213
	v_sub_f32_e32 v141, v141, v213
	v_sub_f32_e32 v142, v142, v213
	v_sub_f32_e32 v143, v143, v213
	v_exp_f32_e32 v140, v140
	v_exp_f32_e32 v141, v141
	v_exp_f32_e32 v142, v142
	v_exp_f32_e32 v143, v143
	v_cvt_pkrtz_f16_f32 v136, v136, v137
	v_cvt_pkrtz_f16_f32 v137, v138, v139
	v_perm_b32 v166, v137, v136, s1
	v_sub_f32_e32 v112, v112, v237
	v_sub_f32_e32 v113, v113, v237
	v_sub_f32_e32 v114, v114, v237
	v_sub_f32_e32 v115, v115, v237
	v_exp_f32_e32 v112, v112
	v_exp_f32_e32 v113, v113
	v_exp_f32_e32 v114, v114
	v_exp_f32_e32 v115, v115
	v_cvt_pkrtz_f16_f32 v140, v140, v141
	v_cvt_pkrtz_f16_f32 v141, v142, v143
	v_perm_b32 v167, v141, v140, s1
	v_sub_f32_e32 v116, v116, v237
	v_sub_f32_e32 v117, v117, v237
	v_sub_f32_e32 v118, v118, v237
	v_sub_f32_e32 v119, v119, v237
	v_exp_f32_e32 v116, v116
	v_exp_f32_e32 v117, v117
	v_exp_f32_e32 v118, v118
	v_exp_f32_e32 v119, v119
	v_cvt_pkrtz_f16_f32 v112, v112, v113
	v_cvt_pkrtz_f16_f32 v113, v114, v115
	v_perm_b32 v148, v113, v112, s1
	v_sub_f32_e32 v120, v120, v237
	v_sub_f32_e32 v121, v121, v237
	v_sub_f32_e32 v122, v122, v237
	v_sub_f32_e32 v123, v123, v237
	v_exp_f32_e32 v120, v120
	v_exp_f32_e32 v121, v121
	v_exp_f32_e32 v122, v122
	v_exp_f32_e32 v123, v123
	v_cvt_pkrtz_f16_f32 v116, v116, v117
	v_cvt_pkrtz_f16_f32 v117, v118, v119
	v_perm_b32 v149, v117, v116, s1
	v_sub_f32_e32 v124, v124, v237
	v_sub_f32_e32 v125, v125, v237
	v_sub_f32_e32 v126, v126, v237
	v_sub_f32_e32 v127, v127, v237
	v_exp_f32_e32 v124, v124
	v_exp_f32_e32 v125, v125
	v_exp_f32_e32 v126, v126
	v_exp_f32_e32 v127, v127
	v_cvt_pkrtz_f16_f32 v120, v120, v121
	v_cvt_pkrtz_f16_f32 v121, v122, v123
	v_perm_b32 v150, v121, v120, s1
	s_nop 0
	v_cvt_pkrtz_f16_f32 v124, v124, v125
	v_cvt_pkrtz_f16_f32 v125, v126, v127
	v_perm_b32 v151, v125, v124, s1
	s_waitcnt vmcnt(0)
	v_add_u32_e32 v112, s99, v250
	ds_write_b128 v112, v[188:191]
	v_add_u32_e32 v113, s100, v250
	ds_write_b128 v113, v[192:195] offset:9216
	v_add_u32_e32 v114, s101, v251
	ds_write2_b32 v114, v222, v223 offset1:8
	v_add_u32_e32 v115, 0x1400, v114
	ds_write2_b32 v115, v220, v221 offset1:8
	s_setprio 3
	s_waitcnt lgkmcnt(4)
	v_mfma_f32_32x32x64_f8f6f4 v[64:79], v[80:87], v[144:151], v[64:79] blgp:1
	v_mfma_f32_32x32x64_f8f6f4 v[96:111], v[80:87], v[160:167], v[96:111] blgp:1
	ds_read_b128 v[80:83], v19 offset:32
	ds_read_b128 v[84:87], v19 offset:64
	v_mfma_f32_32x32x64_f8f6f4 v[48:63], v[88:95], v[160:167], v[48:63] blgp:1
	v_mfma_f32_32x32x64_f8f6f4 v[32:47], v[88:95], v[144:151], v[32:47] blgp:1
	ds_read_b128 v[88:91], v19 offset:96
	ds_read_b128 v[92:95], v19 offset:4608
	v_mfma_f32_16x16x128_f8f6f4 v[196:199], v[2:9], v[160:167], v[196:199] blgp:1
	v_mfma_f32_16x16x128_f8f6f4 v[200:203], v[2:9], v[144:151], v[200:203] blgp:1
	v_mfma_f32_32x32x16_bf16 v[160:175], v[204:207], v[10:13], -4.0
	ds_read_b128 v[204:207], v19 offset:4640
	s_waitcnt lgkmcnt(3)
	v_mfma_f32_32x32x16_bf16 v[160:175], v[80:83], v[176:179], v[160:175]
	v_mfma_f32_32x32x16_bf16 v[144:159], v[84:87], v[180:183], -4.0
	ds_read_b128 v[80:83], v19 offset:4672
	ds_read_b128 v[84:87], v19 offset:4704
	s_waitcnt lgkmcnt(3)
	v_mfma_f32_32x32x16_bf16 v[144:159], v[88:91], v[184:187], v[144:159]
	v_mfma_f32_32x32x16_bf16 v[128:143], v[92:95], v[10:13], -4.0
	s_waitcnt lgkmcnt(0)
	v_mfma_f32_32x32x16_bf16 v[128:143], v[204:207], v[176:179], v[128:143]
	v_mfma_f32_32x32x16_bf16 v[112:127], v[80:83], v[180:183], -4.0
	v_mfma_f32_32x32x16_bf16 v[112:127], v[84:87], v[184:187], v[112:127]
	s_mov_b32 s98, s100
	s_mov_b32 s100, s99
	s_add_i32 s99, s99, 0x4800
	s_cmp_eq_u32 s99, 0x12000
	s_cselect_b32 s99, 0, s99
	s_mov_b32 s7, s101
	s_add_i32 s101, s101, 0x2800
	s_cmp_eq_u32 s101, 0x1c000
	s_cselect_b32 s101, 0x12000, s101
	s_mov_b32 s16, s17
	s_add_i32 s17, s17, 0x80
	s_and_b32 s17, s17, 0x3fff
	v_add_u32_e32 v18, s98, v16
	v_add_u32_e32 v20, s7, v17
	v_add_u32_e32 v19, s100, v16
	s_add_i32 s6, s6, 1
	s_cmpk_lt_u32 s6, 0x80
	s_waitcnt lgkmcnt(0)
	s_barrier
	s_cbranch_scc1 .Ldiff_lag_s_loop
	v_mov_b32_e32 v16, -4.0
	v_mov_b32_e32 v17, -4.0
	v_mov_b32_e32 v18, -4.0
	v_mov_b32_e32 v19, -4.0
	v_mov_b32_e32 v20, -4.0
	v_mov_b32_e32 v21, -4.0
	v_mov_b32_e32 v22, -4.0
	v_mov_b32_e32 v23, -4.0
	v_mov_b32_e32 v24, -4.0
	v_mov_b32_e32 v25, -4.0
	v_mov_b32_e32 v26, -4.0
	v_mov_b32_e32 v27, -4.0
	s_nop 7
	s_branch .LBB0_462
